# layer-0 FFN-out weight conversion moved into the setup phase; mod partials of layer l+1 computed in layer l's out-proj phase and reduced in its FFN-out phase
# baseline (speedup 1.0000x reference)
.LBB0_21:
	v_readlane_b32 s44, v243, 0
	s_and_b32 s0, s44, 0xffffffc0
	s_add_i32 s1, s44, 0xffffff40
	s_cmpk_gt_i32 s44, 0x1bf
	v_writelane_b32 v241, s16, 9
	s_cselect_b32 s1, s1, s44
	s_cmpk_eq_i32 s51, 0x200
	v_writelane_b32 v241, s17, 10
	s_cselect_b32 s2, 0x1c0, s51
	s_cmpk_lg_i32 s0, 0x100
	v_writelane_b32 v241, s18, 11
	s_cselect_b32 s0, s1, 0x6c0
	s_cmpk_eq_i32 s51, 0x200
	s_movk_i32 s1, 0x1200
	v_writelane_b32 v241, s19, 12
	s_cselect_b32 s50, s1, 0x4800
	s_movk_i32 s1, 0xc0
	v_writelane_b32 v241, s2, 13
	s_cselect_b32 s3, s1, 0x300
	v_writelane_b32 v241, s3, 14
	s_cselect_b32 s1, 0x240, 0
	v_writelane_b32 v241, s1, 15
	s_movk_i32 s1, 0xbe0
	s_cselect_b32 s2, s1, 0x2f80
	s_cselect_b32 s0, s0, s44
	s_cmpk_lg_i32 s51, 0x200
	v_writelane_b32 v241, s2, 16
	s_cselect_b64 s[4:5], -1, 0
	s_cmpk_lt_i32 s44, 0x600
	v_writelane_b32 v241, s0, 17
	s_cselect_b64 s[0:1], -1, 0
	v_writelane_b32 v241, s0, 18
	s_lshl_b32 s7, s44, 8
	s_lshl_b32 s47, s51, 8
	v_writelane_b32 v241, s1, 19
	s_lshl_b32 s0, s44, 2
	v_writelane_b32 v241, s0, 20
	s_add_i32 s0, s3, 0x20d
	s_cmp_lt_i32 s44, s0
	v_writelane_b32 v241, s0, 21
	s_cselect_b64 s[0:1], -1, 0
	v_writelane_b32 v241, s0, 22
	s_cmp_lt_i32 s44, s2
	s_cselect_b64 s[2:3], -1, 0
	v_writelane_b32 v241, s1, 23
	s_mul_hi_i32 s0, s44, 0xac769185
	s_add_i32 s0, s0, s44
	s_lshr_b32 s1, s0, 31
	s_ashr_i32 s0, s0, 11
	s_add_i32 s0, s0, s1
	s_mul_i32 s1, s0, 0xbe0
	s_sub_i32 s15, s44, s1
	v_writelane_b32 v241, s2, 24
	s_cmpk_gt_i32 s15, 0x29f
	v_readlane_b32 s16, v243, 53
	v_writelane_b32 v241, s3, 25
	s_cselect_b64 s[2:3], -1, 0
	v_writelane_b32 v241, s2, 26
	s_cmpk_gt_u32 s15, 0x39f
	v_readlane_b32 s28, v242, 1
	v_writelane_b32 v241, s3, 27
	s_cselect_b64 s[2:3], -1, 0
	v_writelane_b32 v241, s2, 28
	s_ashr_i32 s1, s0, 31
	v_readlane_b32 s19, v243, 56
	v_writelane_b32 v241, s3, 29
	s_mul_i32 s2, s0, 0xb00000
	v_readlane_b32 s29, v242, 2
	s_add_u32 s11, s28, s2
	s_mul_hi_i32 s2, s0, 0xb00000
	v_readlane_b32 s26, v243, 63
	s_addc_u32 s12, s29, s2
	s_and_b32 s19, s15, 15
	s_mul_i32 s2, s0, 0x1600000
	v_readlane_b32 s27, v242, 0
	s_add_u32 s13, s26, s2
	s_mul_hi_i32 s2, s0, 0x1600000
	s_addc_u32 s14, s27, s2
	s_add_i32 s2, s15, 0xfc60
	s_and_b32 s3, s2, 0xffff
	v_readlane_b32 s18, v243, 55
	s_mul_i32 s3, s3, 0xba2f
	s_lshr_b32 s18, s3, 22
	s_mul_i32 s3, s18, 0x58
	s_sub_i32 s2, s2, s3
	v_readlane_b32 s20, v243, 57
	s_and_b32 s3, s2, 0xffff
	s_add_i32 s2, s15, 0xfffffd60
	s_lshl_b64 s[8:9], s[0:1], 22
	v_readlane_b32 s21, v243, 58
	s_add_u32 s8, s20, s8
	s_addc_u32 s9, s21, s9
	v_writelane_b32 v241, s8, 30
	s_mul_hi_i32 s1, s0, 0xa80000
	s_mul_i32 s0, s0, 0xa80000
	s_lshr_b32 s2, s2, 4
	v_writelane_b32 v241, s9, 31
	s_add_u32 s0, s58, s0
	v_writelane_b32 v241, s2, 32
	s_addc_u32 s1, s59, s1
	v_writelane_b32 v241, s0, 33
	v_mov_b32_e32 v1, 0x2a0
	v_readlane_b32 s17, v243, 54
	v_writelane_b32 v241, s1, 34
	s_mul_i32 s0, s15, 0xffffc30d
	s_lshr_b32 s0, s0, 16
	s_add_i32 s0, s0, s15
	s_sext_i32_i16 s1, s0
	s_ashr_i32 s1, s1, 5
	s_bfe_u32 s0, s0, 0x1000f
	s_add_i32 s0, s1, s0
	s_mul_i32 s1, s0, 42
	s_sub_i32 s1, s15, s1
	s_cmpk_lt_i32 s44, 0x100
	s_cselect_b64 s[8:9], -1, 0
	v_writelane_b32 v241, s8, 35
	s_or_b64 s[4:5], s[8:9], s[4:5]
	s_add_i32 s2, s44, 0xae0
	v_writelane_b32 v241, s9, 36
	v_writelane_b32 v241, s4, 37
	s_mov_b32 s49, 0
	v_mov_b32_e32 v3, 0x920
	v_writelane_b32 v241, s5, 38
	v_writelane_b32 v241, s2, 39
	s_add_i32 s2, s7, 0xffff1200
	v_writelane_b32 v241, s7, 40
	s_cmpk_lt_i32 s44, 0x580
	v_writelane_b32 v241, s2, 41
	s_cselect_b64 s[4:5], -1, 0
	s_add_i32 s2, s44, 0xffffff00
	v_writelane_b32 v241, s4, 42
	s_cmpk_lt_u32 s2, 0x240
	s_movk_i32 s43, 0x1600
	v_writelane_b32 v241, s5, 43
	s_cselect_b64 s[4:5], -1, 0
	v_writelane_b32 v241, s4, 44
	v_mov_b32_e32 v2, s18
	v_readlane_b32 s22, v243, 59
	v_writelane_b32 v241, s5, 45
	s_add_i32 s4, s44, 0x820
	s_cmpk_lt_i32 s44, 0x3c0
	s_cselect_b64 s[8:9], -1, 0
	s_lshr_b32 s2, s4, 5
	s_mul_hi_u32 s2, s2, 0xac76919
	s_lshr_b32 s48, s2, 2
	v_writelane_b32 v241, s8, 46
	s_mul_i32 s2, s48, 0xbe0
	v_readlane_b32 s23, v243, 60
	v_writelane_b32 v241, s9, 47
	s_sub_i32 s9, s4, s2
	v_sub_co_u32_e32 v1, vcc, s9, v1
	v_writelane_b32 v241, s4, 48
	s_xor_b64 s[4:5], vcc, -1
	v_writelane_b32 v241, s4, 49
	s_cmpk_gt_u32 s9, 0x39f
	s_mul_i32 s2, s48, 0xb00000
	v_writelane_b32 v241, s5, 50
	s_cselect_b64 s[4:5], -1, 0
	v_writelane_b32 v241, s4, 51
	v_sub_co_u32_e32 v4, vcc, s15, v3
	s_nop 0
	v_writelane_b32 v241, s5, 52
	s_add_u32 s4, s28, s2
	s_mul_hi_u32 s2, s48, 0xb00000
	s_addc_u32 s5, s29, s2
	s_and_b32 s42, s9, 15
	s_mul_i32 s2, s48, 0x1600000
	s_add_u32 s7, s26, s2
	s_mul_hi_u32 s2, s48, 0x1600000
	s_addc_u32 s8, s27, s2
	s_add_i32 s2, s9, 0xfc60
	s_and_b32 s10, s2, 0xffff
	s_mul_i32 s10, s10, 0xba2f
	s_lshr_b32 s10, s10, 22
	s_mul_i32 s16, s10, 0x58
	s_sub_i32 s2, s2, s16
	s_and_b32 s2, s2, 0xffff
	s_lshl_b64 s[16:17], s[48:49], 22
	s_add_u32 s16, s20, s16
	s_addc_u32 s17, s21, s17
	v_writelane_b32 v241, s16, 53
	v_lshrrev_b32_e32 v4, 4, v4
	v_readlane_b32 s24, v243, 61
	v_writelane_b32 v241, s17, 54
	s_mul_i32 s17, s48, 0xa80000
	s_mul_hi_u32 s16, s48, 0xa80000
	s_add_u32 s20, s58, s17
	s_addc_u32 s21, s59, s16
	s_bfe_u32 s15, s9, 0xf0001
	v_writelane_b32 v241, s20, 55
	s_mul_i32 s15, s15, 0xc30d
	s_lshr_b32 s15, s15, 20
	v_writelane_b32 v241, s21, 56
	v_writelane_b32 v241, s15, 57
	s_mul_i32 s15, s15, 42
	s_sub_i32 s15, s9, s15
	s_and_b32 s15, s15, 0xffff
	s_cmpk_lt_i32 s44, 0x300
	v_writelane_b32 v241, s15, 58
	s_cselect_b64 s[16:17], -1, 0
	v_writelane_b32 v241, s16, 59
	s_cmpk_lt_i32 s44, 0x1f8
	v_readlane_b32 s25, v243, 62
	v_writelane_b32 v241, s17, 60
	s_cselect_b64 s[16:17], -1, 0
	v_writelane_b32 v241, s16, 61
	s_cmp_eq_u32 s6, 15
	v_readlane_b32 s30, v242, 3
	v_writelane_b32 v241, s17, 62
	s_cselect_b64 s[16:17], -1, 0
	v_writelane_b32 v241, s16, 63
	s_cmp_eq_u32 s6, 14
	v_readlane_b32 s31, v242, 4
	v_writelane_b32 v240, s17, 0
	s_cselect_b64 s[16:17], -1, 0
	v_writelane_b32 v240, s16, 1
	s_cmp_eq_u32 s6, 13
	v_cndmask_b32_e32 v171, v4, v2, vcc
	v_writelane_b32 v240, s17, 2
	s_cselect_b64 s[16:17], -1, 0
	v_writelane_b32 v240, s16, 3
	s_cmp_eq_u32 s6, 12
	v_mov_b32_e32 v2, s10
	v_writelane_b32 v240, s17, 4
	s_cselect_b64 s[16:17], -1, 0
	v_writelane_b32 v240, s16, 5
	s_cmp_eq_u32 s6, 11
	s_sext_i32_i16 s0, s0
	v_writelane_b32 v240, s17, 6
	s_cselect_b64 s[16:17], -1, 0
	v_writelane_b32 v240, s16, 7
	s_cmp_eq_u32 s6, 10
	s_mov_b32 s69, s49
	v_writelane_b32 v240, s17, 8
	s_cselect_b64 s[16:17], -1, 0
	v_writelane_b32 v240, s16, 9
	s_cmp_eq_u32 s6, 9
	v_readlane_b32 s72, v242, 41
	v_writelane_b32 v240, s17, 10
	s_cselect_b64 s[16:17], -1, 0
	v_writelane_b32 v240, s16, 11
	s_cmp_eq_u32 s6, 8
	v_readlane_b32 s74, v242, 43
	v_writelane_b32 v240, s17, 12
	s_cselect_b64 s[16:17], -1, 0
	v_writelane_b32 v240, s16, 13
	s_cmp_eq_u32 s6, 7
	v_readlane_b32 s75, v242, 44
	v_writelane_b32 v240, s17, 14
	s_cselect_b64 s[16:17], -1, 0
	v_writelane_b32 v240, s16, 15
	s_cmp_eq_u32 s6, 6
	v_and_b32_e32 v175, 0x3ff, v0
	v_writelane_b32 v240, s17, 16
	s_cselect_b64 s[16:17], -1, 0
	v_writelane_b32 v240, s16, 17
	s_cmp_eq_u32 s6, 5
	v_readlane_b32 s76, v242, 45
	v_writelane_b32 v240, s17, 18
	s_cselect_b64 s[16:17], -1, 0
	v_writelane_b32 v240, s16, 19
	s_cmp_eq_u32 s6, 4
	v_readlane_b32 s78, v242, 47
	v_writelane_b32 v240, s17, 20
	s_cselect_b64 s[16:17], -1, 0
	v_writelane_b32 v240, s16, 21
	s_cmp_eq_u32 s6, 3
	v_readlane_b32 s80, v242, 49
	v_writelane_b32 v240, s17, 22
	s_cselect_b64 s[16:17], -1, 0
	v_writelane_b32 v240, s16, 23
	s_cmp_eq_u32 s6, 2
	v_readlane_b32 s82, v242, 51
	v_writelane_b32 v240, s17, 24
	s_cselect_b64 s[16:17], -1, 0
	v_writelane_b32 v240, s16, 25
	s_cmp_eq_u32 s6, 1
	v_readlane_b32 s84, v242, 53
	v_writelane_b32 v240, s17, 26
	s_cselect_b64 s[16:17], -1, 0
	v_writelane_b32 v240, s16, 27
	s_cmp_eq_u32 s6, 0
	v_readlane_b32 s86, v242, 55
	v_writelane_b32 v240, s17, 28
	s_cselect_b64 s[16:17], -1, 0
	s_lshl_b32 s6, s6, 6
	v_writelane_b32 v240, s16, 29
	s_add_i32 s48, s6, 0x500
	s_add_i32 s68, s6, 0x900
	s_and_b32 s91, s44, 31
	v_writelane_b32 v240, s17, 30
	s_and_b64 s[16:17], vcc, exec
	s_cselect_b32 s15, s14, s12
	s_cselect_b32 s14, s13, s11
	v_writelane_b32 v240, s14, 31
	s_cselect_b32 s3, s3, s19
	s_cselect_b32 s6, s43, 0x400
	v_writelane_b32 v240, s15, 32
	v_writelane_b32 v240, s19, 33
	v_writelane_b32 v240, s3, 34
	s_lshl_b32 s3, s91, 5
	s_or_b32 s3, s3, 1
	v_writelane_b32 v240, s6, 35
	s_mulk_i32 s3, 0x1800
	v_sub_co_u32_e32 v3, vcc, s9, v3
	v_writelane_b32 v240, s7, 36
	s_add_i32 s6, s3, 0x1800
	s_add_i32 s9, s3, 0x3000
	s_add_i32 s10, s3, 0x4800
	s_or_b32 s11, s3, 0x6000
	s_add_i32 s12, s3, 0x7800
	s_add_i32 s13, s3, 0x9000
	s_lshl_b32 s14, s91, 7
	s_add_u32 s92, s52, s14
	v_readlane_b32 s16, v243, 21
	s_addc_u32 s93, s53, 0
	v_readlane_b32 s30, v243, 35
	v_readlane_b32 s31, v243, 36
	s_add_u32 s30, s30, s14
	s_addc_u32 s31, s31, 0
	s_add_u32 s14, s30, 0x1000
	s_addc_u32 s15, s31, 0
	v_readlane_b32 s17, v243, 22
	v_readlane_b32 s18, v243, 23
	v_readlane_b32 s19, v243, 24
	v_readlane_b32 s20, v243, 25
	v_readlane_b32 s21, v243, 26
	v_readlane_b32 s22, v243, 27
	v_readlane_b32 s23, v243, 28
	v_readlane_b32 s24, v243, 29
	v_readlane_b32 s25, v243, 30
	v_readlane_b32 s26, v243, 31
	v_readlane_b32 s27, v243, 32
	v_readlane_b32 s28, v243, 33
	v_readlane_b32 s29, v243, 34
	v_writelane_b32 v240, s14, 37
	s_add_i32 s16, s3, 0xd800
	s_add_i32 s17, s3, 0xf000
	v_writelane_b32 v240, s15, 38
	s_add_i32 s14, s3, 0xa800
	s_or_b32 s15, s3, 0xc000
	s_add_i32 s18, s3, 0x10800
	s_add_i32 s19, s3, 0x12000
	s_add_i32 s20, s3, 0x13800
	s_add_i32 s21, s3, 0x15000
	s_add_i32 s22, s3, 0x16800
	s_add_i32 s23, s3, 0x18000
	s_add_i32 s24, s3, 0x19800
	s_add_i32 s25, s3, 0x1b000
	s_add_i32 s26, s3, 0x1c800
	s_add_i32 s27, s3, 0x1e000
	s_add_i32 s28, s3, 0x1f800
	s_add_i32 s29, s3, 0x21000
	s_add_u32 s34, s30, 0x1040
	v_writelane_b32 v240, s30, 39
	s_addc_u32 s35, s31, 0
	s_add_i32 s36, s3, 0x28800
	v_writelane_b32 v240, s31, 40
	v_writelane_b32 v240, s34, 41
	s_add_i32 s30, s3, 0x22800
	s_add_i32 s31, s3, 0x24000
	v_writelane_b32 v240, s35, 42
	s_add_i32 s34, s3, 0x25800
	s_add_i32 s35, s3, 0x27000
	s_add_i32 s37, s3, 0x2a000
	s_add_i32 s38, s3, 0x2b800
	s_add_i32 s39, s3, 0x2d000
	s_and_b64 s[40:41], vcc, exec
	s_cselect_b32 s5, s8, s5
	s_cselect_b32 s4, s7, s4
	v_writelane_b32 v240, s4, 43
	v_lshrrev_b32_e32 v3, 4, v3
	v_mbcnt_lo_u32_b32 v0, -1, 0
	v_writelane_b32 v240, s5, 44
	v_writelane_b32 v240, s0, 45
	s_sext_i32_i16 s0, s1
	v_writelane_b32 v240, s0, 46
	v_writelane_b32 v240, s68, 47
	s_cselect_b32 s0, s2, s42
	v_cndmask_b32_e32 v173, v3, v2, vcc
	v_writelane_b32 v240, s69, 48
	v_writelane_b32 v240, s42, 49
	v_writelane_b32 v240, s0, 50
	s_cselect_b32 s0, s43, 0x400
	v_writelane_b32 v240, s0, 51
	v_readlane_b32 s40, v242, 21
	v_readlane_b32 s41, v242, 22
	v_writelane_b32 v240, s1, 52
	s_add_i32 s0, s44, s51
	s_lshl_b32 s0, s0, 2
	v_writelane_b32 v240, s0, 53
	s_lshl_b32 s0, s51, 2
	v_writelane_b32 v240, s0, 54
	s_add_u32 s0, s40, 0x1e00
	s_addc_u32 s1, s41, 0
	v_writelane_b32 v240, s0, 55
	v_readlane_b32 s42, v242, 23
	v_lshrrev_b32_e32 v176, 4, v1
	v_writelane_b32 v240, s1, 56
	s_add_i32 s0, s44, 0xfffffe00
	v_writelane_b32 v240, s0, 57
	v_writelane_b32 v240, s52, 58
	s_mov_b32 s44, s91
	v_mov_b32_e32 v129, 0
	v_writelane_b32 v239, s58, 0
	v_writelane_b32 v239, s59, 1
	v_writelane_b32 v239, s60, 2
	v_writelane_b32 v239, s61, 3
	v_writelane_b32 v239, s62, 4
	v_writelane_b32 v240, s53, 59
	v_writelane_b32 v239, s63, 5
	v_writelane_b32 v240, s54, 60
	v_writelane_b32 v239, s64, 6
	v_writelane_b32 v240, s55, 61
	v_writelane_b32 v239, s65, 7
	v_writelane_b32 v240, s56, 62
	v_writelane_b32 v239, s66, 8
	v_writelane_b32 v240, s57, 63
	v_writelane_b32 v239, s67, 9
	v_readlane_b32 s52, v243, 5
	v_readlane_b32 s60, v243, 13
	v_readlane_b32 s61, v243, 14
	s_add_u32 s0, s60, 0x80
	s_addc_u32 s1, s61, 0
	v_writelane_b32 v239, s0, 10
	v_readlane_b32 s56, v243, 9
	v_readlane_b32 s57, v243, 10
	v_readlane_b32 s58, v243, 11
	v_readlane_b32 s59, v243, 12
	v_readlane_b32 s62, v243, 15
	v_readlane_b32 s63, v243, 16
	v_readlane_b32 s64, v243, 17
	v_readlane_b32 s65, v243, 18
	v_readlane_b32 s66, v243, 19
	v_readlane_b32 s67, v243, 20
	v_writelane_b32 v239, s1, 11
	s_add_u32 s0, s74, 0x80
	v_readlane_b32 s56, v240, 58
	s_addc_u32 s1, s75, 0
	v_readlane_b32 s62, v239, 0
	v_readlane_b32 s63, v239, 1
	v_readlane_b32 s64, v239, 2
	v_readlane_b32 s65, v239, 3
	v_readlane_b32 s66, v239, 4
	v_readlane_b32 s67, v239, 5
	v_readlane_b32 s68, v239, 6
	v_readlane_b32 s69, v239, 7
	v_readlane_b32 s70, v239, 8
	v_readlane_b32 s71, v239, 9
	v_writelane_b32 v239, s0, 12
	s_lshl_b32 s4, s3, 2
	v_cmp_eq_u32_e64 s[2:3], 0, v175
	v_writelane_b32 v239, s1, 13
	s_mul_i32 s0, s91, 0x30000
	v_writelane_b32 v239, s2, 14
	s_lshl_b32 s0, s0, 2
	s_mov_b32 s1, s49
	v_writelane_b32 v239, s3, 15
	v_writelane_b32 v239, s0, 16
	s_lshl_b64 s[48:49], s[48:49], 2
	s_mov_b32 s64, s47
	v_writelane_b32 v239, s1, 17
	v_writelane_b32 v239, s48, 18
	v_readlane_b32 s53, v243, 6
	v_readlane_b32 s54, v243, 7
	v_writelane_b32 v239, s49, 19
	v_writelane_b32 v239, s51, 20
	v_writelane_b32 v239, s50, 21
	v_readlane_b32 s55, v243, 8
	s_mov_b64 s[46:47], s[92:93]
	v_writelane_b32 v239, s64, 22
	v_readlane_b32 s57, v240, 59
	v_readlane_b32 s58, v240, 60
	v_readlane_b32 s59, v240, 61
	v_readlane_b32 s60, v240, 62
	v_readlane_b32 s61, v240, 63
	v_mov_b32_e32 v177, 0x3727c5ac
	v_mov_b64_e32 v[130:131], 0xe8
	v_mov_b32_e32 v178, 0x260
	v_mov_b32_e32 v179, 0x358637bd
	v_mov_b32_e32 v180, 0x3c0881c4
	v_mov_b32_e32 v181, 0xbab64f3b
	v_mov_b32_e32 v182, 0x1000
	v_mov_b32_e32 v183, 0x12000
	v_mov_b32_e32 v184, 0x12004
	v_mov_b32_e32 v185, 1
	v_mov_b32_e32 v186, 2
	v_mov_b32_e32 v187, 0x580000
	v_mov_b32_e32 v188, 0x1600
	v_mov_b32_e32 v189, 0xfffff500
	v_mov_b32_e32 v190, 0xb00000
	v_mbcnt_hi_u32_b32 v191, -1, v0
	v_mov_b32_e32 v192, 0x41b17218
	v_mov_b32_e32 v193, 0x400
	v_mov_b32_e32 v194, 0x600
	v_mov_b32_e32 v195, 0x540000
	v_mov_b32_e32 v196, 0x42800000
	v_not_b32_e32 v197, 63
	v_not_b32_e32 v198, 31
	v_mov_b32_e32 v199, 0x7fc00000
	s_movk_i32 s33, 0x6000
	s_lshl_b32 s6, s6, 2
	s_lshl_b32 s8, s9, 2
	s_lshl_b32 s10, s10, 2
	s_lshl_b32 s40, s11, 2
	s_lshl_b32 s12, s12, 2
	s_lshl_b32 s42, s13, 2
	s_lshl_b32 s14, s14, 2
	s_lshl_b32 s66, s15, 2
	s_lshl_b32 s16, s16, 2
	s_lshl_b32 s70, s17, 2
	s_lshl_b32 s18, s18, 2
	s_lshl_b32 s72, s19, 2
	s_lshl_b32 s20, s20, 2
	s_lshl_b32 s74, s21, 2
	s_lshl_b32 s22, s22, 2
	s_lshl_b32 s78, s23, 2
	s_lshl_b32 s24, s24, 2
	s_lshl_b32 s80, s25, 2
	s_lshl_b32 s26, s26, 2
	s_lshl_b32 s82, s27, 2
	s_lshl_b32 s28, s28, 2
	s_lshl_b32 s84, s29, 2
	s_lshl_b32 s86, s30, 2
	s_lshl_b32 s88, s31, 2
	s_lshl_b32 s34, s34, 2
	s_lshl_b32 s90, s35, 2
	s_lshl_b32 s36, s36, 2
	s_lshl_b32 s76, s37, 2
	s_lshl_b32 s38, s38, 2
	s_lshl_b32 s54, s39, 2
	s_movk_i32 s52, 0x7fff
	s_movk_i32 s55, 0x2a00
	s_mov_b64 s[2:3], 0x80
	s_mov_b64 s[30:31], 0xc0
	s_mov_b32 s53, s91
	v_writelane_b32 v239, s46, 23
	v_readlane_b32 s43, v242, 24
	v_readlane_b32 s73, v242, 42
	v_readlane_b32 s77, v242, 46
	v_readlane_b32 s79, v242, 48
	v_readlane_b32 s81, v242, 50
	v_readlane_b32 s83, v242, 52
	v_readlane_b32 s85, v242, 54
	v_readlane_b32 s87, v242, 56
	v_writelane_b32 v239, s47, 24
	s_branch .LBB0_25

.LBB0_104:
	v_readlane_b32 s4, v241, 9
	s_add_i32 s5, s4, -10
	s_mul_i32 s5, s5, 57
	s_lshr_b32 s5, s5, 9
	s_mul_i32 s5, s5, 0x1200
	s_add_i32 s0, s4, 5
	v_readlane_b32 s4, v241, 41
	s_add_i32 s4, s4, s5
	s_waitcnt vmcnt(0)
	v_add_u32_e32 v14, s4, v132
	s_add_i32 s4, s5, 0x2400
	s_cmp_lt_u32 s0, 35
	v_readlane_b32 s5, v241, 10
	s_cselect_b64 s[0:1], -1, 0
	v_cmp_gt_i32_e32 vcc, s4, v14
	s_and_b64 s[4:5], s[0:1], vcc
	v_readlane_b32 s6, v241, 11
	v_readlane_b32 s7, v241, 12
	s_and_saveexec_b64 s[0:1], s[4:5]
	v_readlane_b32 s8, v243, 5
	v_readlane_b32 s9, v243, 6
	v_readlane_b32 s12, v243, 9
	v_readlane_b32 s13, v243, 10
	v_readlane_b32 s14, v243, 11
	v_readlane_b32 s15, v243, 12
	s_mov_b32 s8, 0x38e38e39
	s_movk_i32 s9, 0x60
	v_readlane_b32 s10, v243, 7
	v_readlane_b32 s11, v243, 8
	v_readlane_b32 s16, v243, 13
	v_readlane_b32 s17, v243, 14
	v_readlane_b32 s18, v243, 15
	v_readlane_b32 s19, v243, 16
	v_readlane_b32 s20, v243, 17
	v_readlane_b32 s21, v243, 18
	v_readlane_b32 s22, v243, 19
	v_readlane_b32 s23, v243, 20
	s_cbranch_execz .LBB0_107
	s_mov_b64 s[4:5], 0

.LBB0_131:
	s_andn2_b64 vcc, exec, s[0:1]
	s_cbranch_vccnz .LBB0_171
	v_readlane_b32 s4, v241, 9
	s_add_i32 s0, s4, 5
	s_cmp_gt_u32 s0, 34
	v_readlane_b32 s5, v241, 10
	v_readlane_b32 s6, v241, 11
	v_readlane_b32 s7, v241, 12
	s_cbranch_scc1 .LBB0_171
	v_readlane_b32 s0, v243, 0
	s_add_i32 s0, s0, 0xffffff00
	s_cmp_lt_u32 s0, 0xc0
	s_cselect_b64 s[0:1], -1, 0
	v_readlane_b32 s16, v238, 21
	v_readlane_b32 s6, v239, 16
	v_readlane_b32 s10, v240, 39
	v_readlane_b32 s17, v238, 22
	s_andn2_b64 vcc, exec, s[0:1]
	v_readlane_b32 s7, v239, 17
	v_readlane_b32 s11, v240, 40
	s_mov_b32 s6, s16
	v_readlane_b32 s36, v238, 5
	v_readlane_b32 s40, v238, 3
	v_readlane_b32 s42, v238, 1
	v_readlane_b32 s48, v239, 63
	v_readlane_b32 s66, v239, 61
	v_readlane_b32 s70, v239, 59
	v_readlane_b32 s72, v239, 57
	v_readlane_b32 s74, v239, 55
	v_readlane_b32 s78, v239, 53
	v_readlane_b32 s16, v239, 51
	v_readlane_b32 s18, v239, 49
	v_readlane_b32 s20, v239, 47
	v_readlane_b32 s22, v239, 45
	v_readlane_b32 s24, v239, 43
	v_readlane_b32 s26, v239, 41
	v_readlane_b32 s96, v239, 39
	v_readlane_b32 s28, v239, 37
	v_readlane_b32 s38, v239, 35
	v_readlane_b32 s8, v239, 33
	v_readlane_b32 s34, v239, 31
	v_readlane_b32 s76, v239, 29
	v_readlane_b32 s12, v239, 27
	v_readlane_b32 s14, v239, 25
	v_readlane_b32 s37, v238, 6
	v_readlane_b32 s41, v238, 4
	v_readlane_b32 s43, v238, 2
	v_readlane_b32 s49, v238, 0
	v_readlane_b32 s67, v239, 62
	v_readlane_b32 s71, v239, 60
	v_readlane_b32 s73, v239, 58
	v_readlane_b32 s75, v239, 56
	v_readlane_b32 s79, v239, 54
	v_readlane_b32 s17, v239, 52
	v_readlane_b32 s19, v239, 50
	v_readlane_b32 s21, v239, 48
	v_readlane_b32 s23, v239, 46
	v_readlane_b32 s25, v239, 44
	v_readlane_b32 s27, v239, 42
	v_readlane_b32 s97, v239, 40
	v_readlane_b32 s29, v239, 38
	v_readlane_b32 s39, v239, 36
	v_readlane_b32 s9, v239, 34
	v_readlane_b32 s35, v239, 32
	v_readlane_b32 s77, v239, 30
	v_readlane_b32 s13, v239, 28
	v_readlane_b32 s15, v239, 26
	s_cbranch_vccnz .LBB0_136
	s_waitcnt vmcnt(0)
	v_lshlrev_b32_e32 v73, 2, v132
	v_readlane_b32 s0, v240, 57
	v_readlane_b32 s1, v241, 9
	s_add_i32 s1, s1, -7
	s_mul_i32 s1, s1, 57
	s_lshr_b32 s1, s1, 9
	s_mul_i32 s1, s1, 0xc0
	s_add_i32 s0, s0, s1
.LBB0_135:
	s_add_i32 s4, s0, 0x1c0
	s_mul_hi_u32 s1, s4, 0xaaaaaaab
	s_lshr_b32 s4, s4, 5
	s_mul_hi_u32 s5, s4, 0x2aaaaaab
	s_mul_i32 s5, s5, 6
	s_sub_i32 s4, s4, s5
	v_lshl_add_u32 v0, s4, 10, v73
	v_ashrrev_i32_e32 v1, 31, v0
	v_lshlrev_b64 v[44:45], 2, v[0:1]
	global_load_dwordx4 v[0:3], v129, s[46:47] offset:48
	global_load_dwordx4 v[12:15], v129, s[46:47] offset:32
	global_load_dwordx4 v[24:27], v129, s[46:47] offset:16
	global_load_dwordx4 v[52:55], v129, s[46:47]
	s_lshr_b32 s1, s1, 7
	s_mul_i32 s4, s1, 0x1800000
	s_mul_hi_u32 s5, s1, 0x1800000
	s_add_u32 s4, s58, s4
	s_addc_u32 s5, s59, s5
	v_lshl_add_u64 v[46:47], s[4:5], 0, v[44:45]
	s_mov_b32 s4, s6
	s_mov_b32 s5, s7
	v_lshl_add_u64 v[36:37], v[46:47], 0, s[4:5]
	v_readlane_b32 s4, v238, 19
	s_mov_b32 s80, s4
	v_readlane_b32 s5, v238, 20
	v_writelane_b32 v238, s80, 19
	s_mov_b32 s5, s7
	v_lshl_add_u64 v[38:39], v[46:47], 0, s[4:5]
	v_writelane_b32 v238, s81, 20
	s_mov_b32 s37, s7
	v_readlane_b32 s4, v238, 17
	s_mov_b32 s80, s4
	v_readlane_b32 s5, v238, 18
	v_writelane_b32 v238, s80, 17
	s_mov_b32 s5, s7
	v_lshl_add_u64 v[40:41], v[46:47], 0, s[4:5]
	v_writelane_b32 v238, s81, 18
	s_mov_b32 s41, s7
	v_readlane_b32 s4, v238, 15
	s_mov_b32 s80, s4
	v_readlane_b32 s5, v238, 16
	v_writelane_b32 v238, s80, 15
	s_mov_b32 s5, s7
	v_lshl_add_u64 v[42:43], v[46:47], 0, s[4:5]
	v_writelane_b32 v238, s81, 16
	v_lshl_add_u64 v[124:125], v[46:47], 0, s[36:37]
	v_readlane_b32 s4, v238, 13
	s_mov_b32 s80, s4
	v_readlane_b32 s5, v238, 14
	v_writelane_b32 v238, s80, 13
	s_mov_b32 s5, s7
	v_lshl_add_u64 v[48:49], v[46:47], 0, s[4:5]
	v_writelane_b32 v238, s81, 14
	v_lshl_add_u64 v[134:135], v[46:47], 0, s[40:41]
	v_readlane_b32 s4, v238, 11
	s_mov_b32 s80, s4
	v_readlane_b32 s5, v238, 12
	v_writelane_b32 v238, s80, 11
	s_mov_b32 s5, s7
	v_lshl_add_u64 v[50:51], v[46:47], 0, s[4:5]
	v_writelane_b32 v238, s81, 12
	s_mov_b32 s43, s7
	v_readlane_b32 s4, v238, 9
	s_mov_b32 s80, s4
	v_readlane_b32 s5, v238, 10
	v_writelane_b32 v238, s80, 9
	s_mov_b32 s5, s7
	v_lshl_add_u64 v[62:63], v[46:47], 0, s[4:5]
	v_writelane_b32 v238, s81, 10
	s_mov_b32 s49, s7
	v_readlane_b32 s4, v238, 7
	v_readlane_b32 s5, v238, 8
	s_mov_b32 s5, s7
	s_mov_b32 s80, s4
	v_lshl_add_u64 v[64:65], v[46:47], 0, s[4:5]
	s_mov_b32 s67, s7
	s_mov_b32 s71, s7
	s_mov_b32 s73, s7
	s_mov_b32 s75, s7
	s_mov_b32 s79, s7
	s_mov_b32 s17, s7
	s_mov_b32 s19, s7
	s_mov_b32 s21, s7
	s_mov_b32 s23, s7
	s_mov_b32 s25, s7
	s_mov_b32 s27, s7
	s_mov_b32 s97, s7
	s_mov_b32 s29, s7
	s_mov_b32 s39, s7
	s_mov_b32 s9, s7
	s_mov_b32 s35, s7
	s_mov_b32 s77, s7
	s_waitcnt vmcnt(0)
	v_mul_f32_e32 v4, 0xbfb8aa3b, v52
	v_exp_f32_e32 v4, v4
	s_mov_b32 s13, s7
	s_mov_b32 s15, s7
	s_mov_b32 s55, s7
	v_add_f32_e32 v4, 1.0, v4
	v_div_scale_f32 v5, s[4:5], v4, v4, v52
	v_rcp_f32_e32 v6, v5
	v_writelane_b32 v238, s80, 7
	s_lshl_b32 s1, s1, 5
	s_or_b32 s1, s1, s44
	v_fma_f32 v7, -v5, v6, 1.0
	v_fmac_f32_e32 v6, v7, v6
	v_div_scale_f32 v7, vcc, v52, v4, v52
	v_mul_f32_e32 v8, v7, v6
	v_fma_f32 v9, -v5, v8, v7
	v_fmac_f32_e32 v8, v9, v6
	v_fma_f32 v5, -v5, v8, v7
	v_div_fmas_f32 v5, v5, v6, v8
	v_div_fixup_f32 v66, v5, v4, v52
	global_load_dwordx4 v[4:7], v129, s[10:11] offset:48
	global_load_dwordx4 v[16:19], v129, s[10:11] offset:32
	global_load_dwordx4 v[28:31], v129, s[10:11] offset:16
	global_load_dwordx4 v[56:59], v129, s[10:11]
	v_writelane_b32 v238, s81, 8
	v_readlane_b32 s80, v243, 5
	v_readlane_b32 s84, v243, 9
	v_readlane_b32 s85, v243, 10
	v_readlane_b32 s81, v243, 6
	v_readlane_b32 s82, v243, 7
	v_readlane_b32 s83, v243, 8
	v_readlane_b32 s86, v243, 11
	v_readlane_b32 s87, v243, 12
	v_readlane_b32 s88, v243, 13
	v_readlane_b32 s89, v243, 14
	v_readlane_b32 s90, v243, 15
	v_readlane_b32 s91, v243, 16
	v_readlane_b32 s92, v243, 17
	v_readlane_b32 s93, v243, 18
	v_readlane_b32 s94, v243, 19
	v_readlane_b32 s95, v243, 20
	s_waitcnt vmcnt(0)
	v_mul_f32_e32 v8, 0xbfb8aa3b, v56
	v_exp_f32_e32 v8, v8
	s_nop 0
	v_add_f32_e32 v8, 1.0, v8
	v_div_scale_f32 v9, s[4:5], v8, v8, v56
	v_rcp_f32_e32 v10, v9
	v_readlane_b32 s4, v240, 37
	v_readlane_b32 s5, v240, 38
	v_fma_f32 v11, -v9, v10, 1.0
	v_fmac_f32_e32 v10, v11, v10
	v_div_scale_f32 v11, vcc, v56, v8, v56
	v_mul_f32_e32 v20, v11, v10
	v_fma_f32 v21, -v9, v20, v11
	v_fmac_f32_e32 v20, v21, v10
	v_fma_f32 v9, -v9, v20, v11
	v_div_fmas_f32 v9, v9, v10, v20
	v_div_fixup_f32 v72, v9, v8, v56
	global_load_dwordx4 v[8:11], v129, s[4:5] offset:48
	global_load_dwordx4 v[20:23], v129, s[4:5] offset:32
	global_load_dwordx4 v[32:35], v129, s[4:5] offset:16
	global_load_dwordx4 v[78:81], v129, s[4:5]
	global_load_dwordx4 v[104:107], v[36:37], off
	s_nop 0
	global_load_dwordx4 v[36:39], v[38:39], off
	s_nop 0
	global_load_dwordx4 v[108:111], v[40:41], off
	s_nop 0
	global_load_dwordx4 v[40:43], v[42:43], off
	s_nop 0
	global_load_dwordx4 v[112:115], v[48:49], off
	s_nop 0
	global_load_dwordx4 v[48:51], v[50:51], off
	s_nop 0
	global_load_dwordx4 v[116:119], v[62:63], off
	global_load_dwordx4 v[120:123], v[64:65], off
	s_nop 0
	global_load_dwordx4 v[124:127], v[124:125], off
	s_nop 0
	global_load_dwordx4 v[134:137], v[134:135], off
	s_waitcnt vmcnt(10)
	v_mul_f32_e32 v52, 0xbfb8aa3b, v78
	v_exp_f32_e32 v52, v52
	s_nop 0
	v_add_f32_e32 v52, 1.0, v52
	v_div_scale_f32 v56, s[4:5], v52, v52, v78
	v_rcp_f32_e32 v60, v56
	s_nop 0
	v_fma_f32 v61, -v56, v60, 1.0
	v_fmac_f32_e32 v60, v61, v60
	v_div_scale_f32 v61, vcc, v78, v52, v78
	v_mul_f32_e32 v67, v61, v60
	v_fma_f32 v68, -v56, v67, v61
	v_fmac_f32_e32 v67, v68, v60
	v_fma_f32 v56, -v56, v67, v61
	v_div_fmas_f32 v56, v56, v60, v67
	v_div_fixup_f32 v74, v56, v52, v78
	v_mul_f32_e32 v52, 0xbfb8aa3b, v53
	v_exp_f32_e32 v52, v52
	s_nop 0
	v_add_f32_e32 v52, 1.0, v52
	v_div_scale_f32 v56, s[4:5], v52, v52, v53
	v_rcp_f32_e32 v60, v56
	s_nop 0
	v_fma_f32 v61, -v56, v60, 1.0
	v_fmac_f32_e32 v60, v61, v60
	v_div_scale_f32 v61, vcc, v53, v52, v53
	v_mul_f32_e32 v67, v61, v60
	v_fma_f32 v68, -v56, v67, v61
	v_fmac_f32_e32 v67, v68, v60
	v_fma_f32 v56, -v56, v67, v61
	v_div_fmas_f32 v56, v56, v60, v67
	v_div_fixup_f32 v68, v56, v52, v53
	v_mul_f32_e32 v52, 0xbfb8aa3b, v57
	v_exp_f32_e32 v52, v52
	s_nop 0
	v_add_f32_e32 v52, 1.0, v52
	v_div_scale_f32 v53, s[4:5], v52, v52, v57
	v_rcp_f32_e32 v56, v53
	s_nop 0
	v_fma_f32 v60, -v53, v56, 1.0
	v_fmac_f32_e32 v56, v60, v56
	v_div_scale_f32 v60, vcc, v57, v52, v57
	v_mul_f32_e32 v61, v60, v56
	v_fma_f32 v67, -v53, v61, v60
	v_fmac_f32_e32 v61, v67, v56
	v_fma_f32 v53, -v53, v61, v60
	v_div_fmas_f32 v53, v53, v56, v61
	v_div_fixup_f32 v78, v53, v52, v57
	v_mul_f32_e32 v52, 0xbfb8aa3b, v79
	v_exp_f32_e32 v52, v52
	s_nop 0
	v_add_f32_e32 v52, 1.0, v52
	v_div_scale_f32 v53, s[4:5], v52, v52, v79
	v_rcp_f32_e32 v56, v53
	s_nop 0
	v_fma_f32 v57, -v53, v56, 1.0
	v_fmac_f32_e32 v56, v57, v56
	v_div_scale_f32 v57, vcc, v79, v52, v79
	v_mul_f32_e32 v60, v57, v56
	v_fma_f32 v61, -v53, v60, v57
	v_fmac_f32_e32 v60, v61, v56
	v_fma_f32 v53, -v53, v60, v57
	v_div_fmas_f32 v53, v53, v56, v60
	v_div_fixup_f32 v76, v53, v52, v79
	v_mul_f32_e32 v52, 0xbfb8aa3b, v54
	v_exp_f32_e32 v52, v52
	s_nop 0
	v_add_f32_e32 v52, 1.0, v52
	v_div_scale_f32 v53, s[4:5], v52, v52, v54
	v_rcp_f32_e32 v56, v53
	s_nop 0
	v_fma_f32 v57, -v53, v56, 1.0
	v_fmac_f32_e32 v56, v57, v56
	v_div_scale_f32 v57, vcc, v54, v52, v54
	v_mul_f32_e32 v60, v57, v56
	v_fma_f32 v61, -v53, v60, v57
	v_fmac_f32_e32 v60, v61, v56
	v_fma_f32 v53, -v53, v60, v57
	v_div_fmas_f32 v53, v53, v56, v60
	v_div_fixup_f32 v70, v53, v52, v54
	v_mul_f32_e32 v52, 0xbfb8aa3b, v58
	v_exp_f32_e32 v52, v52
	s_nop 0
	v_add_f32_e32 v52, 1.0, v52
	v_div_scale_f32 v53, s[4:5], v52, v52, v58
	v_rcp_f32_e32 v54, v53
	s_nop 0
	v_fma_f32 v56, -v53, v54, 1.0
	v_fmac_f32_e32 v54, v56, v54
	v_div_scale_f32 v56, vcc, v58, v52, v58
	v_mul_f32_e32 v57, v56, v54
	v_fma_f32 v60, -v53, v57, v56
	v_fmac_f32_e32 v57, v60, v54
	v_fma_f32 v53, -v53, v57, v56
	v_div_fmas_f32 v53, v53, v54, v57
	v_div_fixup_f32 v82, v53, v52, v58
	v_mul_f32_e32 v52, 0xbfb8aa3b, v80
	v_exp_f32_e32 v52, v52
	v_lshl_add_u64 v[60:61], v[46:47], 0, s[74:75]
	v_add_f32_e32 v52, 1.0, v52
	v_div_scale_f32 v53, s[4:5], v52, v52, v80
	v_rcp_f32_e32 v54, v53
	s_nop 0
	v_fma_f32 v56, -v53, v54, 1.0
	v_fmac_f32_e32 v54, v56, v54
	v_div_scale_f32 v56, vcc, v80, v52, v80
	v_mul_f32_e32 v57, v56, v54
	v_fma_f32 v58, -v53, v57, v56
	v_fmac_f32_e32 v57, v58, v54
	v_fma_f32 v53, -v53, v57, v56
	v_div_fmas_f32 v53, v53, v54, v57
	v_div_fixup_f32 v80, v53, v52, v80
	v_mul_f32_e32 v52, 0xbfb8aa3b, v55
	v_exp_f32_e32 v52, v52
	s_nop 0
	v_add_f32_e32 v52, 1.0, v52
	v_div_scale_f32 v53, s[4:5], v52, v52, v55
	v_rcp_f32_e32 v54, v53
	s_nop 0
	v_fma_f32 v56, -v53, v54, 1.0
	v_fmac_f32_e32 v54, v56, v54
	v_div_scale_f32 v56, vcc, v55, v52, v55
	v_mul_f32_e32 v57, v56, v54
	v_fma_f32 v58, -v53, v57, v56
	v_fmac_f32_e32 v57, v58, v54
	v_fma_f32 v53, -v53, v57, v56
	v_div_fmas_f32 v53, v53, v54, v57
	v_div_fixup_f32 v88, v53, v52, v55
	v_mul_f32_e32 v52, 0xbfb8aa3b, v59
	v_exp_f32_e32 v52, v52
	s_nop 0
	v_add_f32_e32 v52, 1.0, v52
	v_div_scale_f32 v53, s[4:5], v52, v52, v59
	v_rcp_f32_e32 v54, v53
	s_nop 0
	v_fma_f32 v55, -v53, v54, 1.0
	v_fmac_f32_e32 v54, v55, v54
	v_div_scale_f32 v55, vcc, v59, v52, v59
	v_mul_f32_e32 v56, v55, v54
	v_fma_f32 v57, -v53, v56, v55
	v_fmac_f32_e32 v56, v57, v54
	v_fma_f32 v53, -v53, v56, v55
	v_div_fmas_f32 v53, v53, v54, v56
	v_div_fixup_f32 v86, v53, v52, v59
	v_mul_f32_e32 v52, 0xbfb8aa3b, v81
	v_exp_f32_e32 v52, v52
	v_lshl_add_u64 v[58:59], v[46:47], 0, s[72:73]
	v_add_f32_e32 v52, 1.0, v52
	v_div_scale_f32 v53, s[4:5], v52, v52, v81
	v_rcp_f32_e32 v54, v53
	s_nop 0
	v_fma_f32 v55, -v53, v54, 1.0
	v_fmac_f32_e32 v54, v55, v54
	v_div_scale_f32 v55, vcc, v81, v52, v81
	v_mul_f32_e32 v56, v55, v54
	v_fma_f32 v57, -v53, v56, v55
	v_fmac_f32_e32 v56, v57, v54
	v_fma_f32 v53, -v53, v56, v55
	v_div_fmas_f32 v53, v53, v54, v56
	v_div_fixup_f32 v84, v53, v52, v81
	v_mul_f32_e32 v52, 0xbfb8aa3b, v24
	v_exp_f32_e32 v52, v52
	s_nop 0
	v_add_f32_e32 v52, 1.0, v52
	v_div_scale_f32 v53, s[4:5], v52, v52, v24
	v_rcp_f32_e32 v54, v53
	s_nop 0
	v_fma_f32 v55, -v53, v54, 1.0
	v_fmac_f32_e32 v54, v55, v54
	v_div_scale_f32 v55, vcc, v24, v52, v24
	v_mul_f32_e32 v56, v55, v54
	v_fma_f32 v57, -v53, v56, v55
	v_fmac_f32_e32 v56, v57, v54
	v_fma_f32 v53, -v53, v56, v55
	v_div_fmas_f32 v53, v53, v54, v56
	v_div_fixup_f32 v90, v53, v52, v24
	v_mul_f32_e32 v24, 0xbfb8aa3b, v28
	v_exp_f32_e32 v24, v24
	s_nop 0
	v_add_f32_e32 v24, 1.0, v24
	v_div_scale_f32 v52, s[4:5], v24, v24, v28
	v_rcp_f32_e32 v53, v52
	s_nop 0
	v_fma_f32 v54, -v52, v53, 1.0
	v_fmac_f32_e32 v53, v54, v53
	v_div_scale_f32 v54, vcc, v28, v24, v28
	v_mul_f32_e32 v55, v54, v53
	v_fma_f32 v56, -v52, v55, v54
	v_fmac_f32_e32 v55, v56, v53
	v_fma_f32 v52, -v52, v55, v54
	v_div_fmas_f32 v52, v52, v53, v55
	v_div_fixup_f32 v28, v52, v24, v28
	v_mul_f32_e32 v24, 0xbfb8aa3b, v32
	v_exp_f32_e32 v24, v24
	s_nop 0
	v_add_f32_e32 v24, 1.0, v24
	v_div_scale_f32 v52, s[4:5], v24, v24, v32
	v_rcp_f32_e32 v53, v52
	s_nop 0
	v_fma_f32 v54, -v52, v53, 1.0
	v_fmac_f32_e32 v53, v54, v53
	v_div_scale_f32 v54, vcc, v32, v24, v32
	v_mul_f32_e32 v55, v54, v53
	v_fma_f32 v56, -v52, v55, v54
	v_fmac_f32_e32 v55, v56, v53
	v_fma_f32 v52, -v52, v55, v54
	v_div_fmas_f32 v52, v52, v53, v55
	v_div_fixup_f32 v32, v52, v24, v32
	v_mul_f32_e32 v24, 0xbfb8aa3b, v25
	v_exp_f32_e32 v24, v24
	s_nop 0
	v_add_f32_e32 v24, 1.0, v24
	v_div_scale_f32 v52, s[4:5], v24, v24, v25
	v_rcp_f32_e32 v53, v52
	s_nop 0
	v_fma_f32 v54, -v52, v53, 1.0
	v_fmac_f32_e32 v53, v54, v53
	v_div_scale_f32 v54, vcc, v25, v24, v25
	v_mul_f32_e32 v55, v54, v53
	v_fma_f32 v56, -v52, v55, v54
	v_fmac_f32_e32 v55, v56, v53
	v_fma_f32 v52, -v52, v55, v54
	v_div_fmas_f32 v52, v52, v53, v55
	v_div_fixup_f32 v96, v52, v24, v25
	v_mul_f32_e32 v24, 0xbfb8aa3b, v29
	v_exp_f32_e32 v24, v24
	v_lshl_add_u64 v[56:57], v[46:47], 0, s[70:71]
	v_add_f32_e32 v24, 1.0, v24
	v_div_scale_f32 v25, s[4:5], v24, v24, v29
	v_rcp_f32_e32 v52, v25
	s_nop 0
	v_fma_f32 v53, -v25, v52, 1.0
	v_fmac_f32_e32 v52, v53, v52
	v_div_scale_f32 v53, vcc, v29, v24, v29
	v_mul_f32_e32 v54, v53, v52
	v_fma_f32 v55, -v25, v54, v53
	v_fmac_f32_e32 v54, v55, v52
	v_fma_f32 v25, -v25, v54, v53
	v_div_fmas_f32 v25, v25, v52, v54
	v_div_fixup_f32 v94, v25, v24, v29
	v_mul_f32_e32 v24, 0xbfb8aa3b, v33
	v_exp_f32_e32 v24, v24
	s_nop 0
	v_add_f32_e32 v24, 1.0, v24
	v_div_scale_f32 v25, s[4:5], v24, v24, v33
	v_rcp_f32_e32 v29, v25
	s_nop 0
	v_fma_f32 v52, -v25, v29, 1.0
	v_fmac_f32_e32 v29, v52, v29
	v_div_scale_f32 v52, vcc, v33, v24, v33
	v_mul_f32_e32 v53, v52, v29
	v_fma_f32 v54, -v25, v53, v52
	v_fmac_f32_e32 v53, v54, v29
	v_fma_f32 v25, -v25, v53, v52
	v_div_fmas_f32 v25, v25, v29, v53
	v_div_fixup_f32 v92, v25, v24, v33
	v_mul_f32_e32 v24, 0xbfb8aa3b, v26
	v_exp_f32_e32 v24, v24
	v_lshl_add_u64 v[54:55], v[46:47], 0, s[66:67]
	v_add_f32_e32 v24, 1.0, v24
	v_div_scale_f32 v25, s[4:5], v24, v24, v26
	v_rcp_f32_e32 v29, v25
	s_nop 0
	v_fma_f32 v33, -v25, v29, 1.0
	v_fmac_f32_e32 v29, v33, v29
	v_div_scale_f32 v33, vcc, v26, v24, v26
	v_mul_f32_e32 v52, v33, v29
	v_fma_f32 v53, -v25, v52, v33
	v_fmac_f32_e32 v52, v53, v29
	v_fma_f32 v25, -v25, v52, v33
	v_div_fmas_f32 v25, v25, v29, v52
	v_div_fixup_f32 v98, v25, v24, v26
	v_mul_f32_e32 v24, 0xbfb8aa3b, v30
	v_exp_f32_e32 v24, v24
	s_nop 0
	v_add_f32_e32 v24, 1.0, v24
	v_div_scale_f32 v25, s[4:5], v24, v24, v30
	v_rcp_f32_e32 v26, v25
	s_nop 0
	v_fma_f32 v29, -v25, v26, 1.0
	v_fmac_f32_e32 v26, v29, v26
	v_div_scale_f32 v29, vcc, v30, v24, v30
	v_mul_f32_e32 v33, v29, v26
	v_fma_f32 v52, -v25, v33, v29
	v_fmac_f32_e32 v33, v52, v26
	v_fma_f32 v25, -v25, v33, v29
	v_div_fmas_f32 v25, v25, v26, v33
	v_div_fixup_f32 v30, v25, v24, v30
	v_mul_f32_e32 v24, 0xbfb8aa3b, v34
	v_exp_f32_e32 v24, v24
	s_nop 0
	v_add_f32_e32 v24, 1.0, v24
	v_div_scale_f32 v25, s[4:5], v24, v24, v34
	v_rcp_f32_e32 v26, v25
	s_nop 0
	v_fma_f32 v29, -v25, v26, 1.0
	v_fmac_f32_e32 v26, v29, v26
	v_div_scale_f32 v29, vcc, v34, v24, v34
	v_mul_f32_e32 v33, v29, v26
	v_fma_f32 v52, -v25, v33, v29
	v_fmac_f32_e32 v33, v52, v26
	v_fma_f32 v25, -v25, v33, v29
	v_div_fmas_f32 v25, v25, v26, v33
	v_div_fixup_f32 v26, v25, v24, v34
	v_mul_f32_e32 v24, 0xbfb8aa3b, v27
	v_exp_f32_e32 v24, v24
	s_nop 0
	v_add_f32_e32 v24, 1.0, v24
	v_div_scale_f32 v25, s[4:5], v24, v24, v27
	v_rcp_f32_e32 v29, v25
	s_nop 0
	v_fma_f32 v33, -v25, v29, 1.0
	v_fmac_f32_e32 v29, v33, v29
	v_div_scale_f32 v33, vcc, v27, v24, v27
	v_mul_f32_e32 v34, v33, v29
	v_fma_f32 v52, -v25, v34, v33
	v_fmac_f32_e32 v34, v52, v29
	v_fma_f32 v25, -v25, v34, v33
	v_div_fmas_f32 v25, v25, v29, v34
	v_div_fixup_f32 v102, v25, v24, v27
	v_mul_f32_e32 v24, 0xbfb8aa3b, v31
	v_exp_f32_e32 v24, v24
	v_lshl_add_u64 v[52:53], v[46:47], 0, s[48:49]
	v_add_f32_e32 v24, 1.0, v24
	v_div_scale_f32 v25, s[4:5], v24, v24, v31
	v_rcp_f32_e32 v27, v25
	s_nop 0
	v_fma_f32 v29, -v25, v27, 1.0
	v_fmac_f32_e32 v27, v29, v27
	v_div_scale_f32 v29, vcc, v31, v24, v31
	v_mul_f32_e32 v33, v29, v27
	v_fma_f32 v34, -v25, v33, v29
	v_fmac_f32_e32 v33, v34, v27
	v_fma_f32 v25, -v25, v33, v29
	v_div_fmas_f32 v25, v25, v27, v33
	v_div_fixup_f32 v100, v25, v24, v31
	v_mul_f32_e32 v24, 0xbfb8aa3b, v35
	v_exp_f32_e32 v24, v24
	s_nop 0
	v_add_f32_e32 v24, 1.0, v24
	v_div_scale_f32 v25, s[4:5], v24, v24, v35
	v_rcp_f32_e32 v27, v25
	s_nop 0
	v_fma_f32 v29, -v25, v27, 1.0
	v_fmac_f32_e32 v27, v29, v27
	v_div_scale_f32 v29, vcc, v35, v24, v35
	v_mul_f32_e32 v31, v29, v27
	v_fma_f32 v33, -v25, v31, v29
	v_fmac_f32_e32 v31, v33, v27
	v_fma_f32 v25, -v25, v31, v29
	v_div_fmas_f32 v25, v25, v27, v31
	v_mul_f32_e32 v27, 0xbfb8aa3b, v12
	v_exp_f32_e32 v27, v27
	v_div_fixup_f32 v34, v25, v24, v35
	v_lshl_add_u64 v[24:25], v[46:47], 0, s[42:43]
	v_add_f32_e32 v27, 1.0, v27
	v_div_scale_f32 v29, s[4:5], v27, v27, v12
	v_rcp_f32_e32 v31, v29
	s_nop 0
	v_fma_f32 v33, -v29, v31, 1.0
	v_fmac_f32_e32 v31, v33, v31
	v_div_scale_f32 v33, vcc, v12, v27, v12
	v_mul_f32_e32 v35, v33, v31
	v_fma_f32 v67, -v29, v35, v33
	v_fmac_f32_e32 v35, v67, v31
	v_fma_f32 v29, -v29, v35, v33
	v_div_fmas_f32 v29, v29, v31, v35
	v_div_fixup_f32 v12, v29, v27, v12
	v_mul_f32_e32 v27, 0xbfb8aa3b, v16
	v_exp_f32_e32 v27, v27
	s_nop 0
	v_add_f32_e32 v27, 1.0, v27
	v_div_scale_f32 v29, s[4:5], v27, v27, v16
	v_rcp_f32_e32 v31, v29
	s_nop 0
	v_fma_f32 v33, -v29, v31, 1.0
	v_fmac_f32_e32 v31, v33, v31
	v_div_scale_f32 v33, vcc, v16, v27, v16
	v_mul_f32_e32 v35, v33, v31
	v_fma_f32 v67, -v29, v35, v33
	v_fmac_f32_e32 v35, v67, v31
	v_fma_f32 v29, -v29, v35, v33
	v_div_fmas_f32 v29, v29, v31, v35
	v_div_fixup_f32 v16, v29, v27, v16
	v_mul_f32_e32 v27, 0xbfb8aa3b, v20
	v_exp_f32_e32 v27, v27
	s_nop 0
	v_add_f32_e32 v27, 1.0, v27
	v_div_scale_f32 v29, s[4:5], v27, v27, v20
	v_rcp_f32_e32 v31, v29
	s_nop 0
	v_fma_f32 v33, -v29, v31, 1.0
	v_fmac_f32_e32 v31, v33, v31
	v_div_scale_f32 v33, vcc, v20, v27, v20
	v_mul_f32_e32 v35, v33, v31
	v_fma_f32 v67, -v29, v35, v33
	v_fmac_f32_e32 v35, v67, v31
	v_fma_f32 v29, -v29, v35, v33
	v_div_fmas_f32 v29, v29, v31, v35
	v_div_fixup_f32 v20, v29, v27, v20
	v_mul_f32_e32 v27, 0xbfb8aa3b, v13
	v_exp_f32_e32 v27, v27
	s_nop 0
	v_add_f32_e32 v27, 1.0, v27
	v_div_scale_f32 v29, s[4:5], v27, v27, v13
	v_rcp_f32_e32 v31, v29
	s_nop 0
	v_fma_f32 v33, -v29, v31, 1.0
	v_fmac_f32_e32 v31, v33, v31
	v_div_scale_f32 v33, vcc, v13, v27, v13
	v_mul_f32_e32 v35, v33, v31
	v_fma_f32 v67, -v29, v35, v33
	v_fmac_f32_e32 v35, v67, v31
	v_fma_f32 v29, -v29, v35, v33
	v_div_fmas_f32 v29, v29, v31, v35
	v_div_fixup_f32 v128, v29, v27, v13
	v_mul_f32_e32 v13, 0xbfb8aa3b, v17
	v_exp_f32_e32 v13, v13
	s_waitcnt vmcnt(9)
	v_pk_fma_f32 v[62:63], v[104:105], v[66:67], 0 op_sel_hi:[1,0,0]
	v_pk_fma_f32 v[64:65], v[106:107], v[66:67], 0 op_sel_hi:[1,0,0]
	s_waitcnt vmcnt(8)
	v_pk_fma_f32 v[62:63], v[36:37], v[68:69], v[62:63] op_sel_hi:[1,0,1]
	v_add_f32_e32 v13, 1.0, v13
	v_div_scale_f32 v27, s[4:5], v13, v13, v17
	v_rcp_f32_e32 v29, v27
	v_pk_fma_f32 v[64:65], v[38:39], v[68:69], v[64:65] op_sel_hi:[1,0,1]
	s_waitcnt vmcnt(7)
	v_pk_fma_f32 v[62:63], v[108:109], v[70:71], v[62:63] op_sel_hi:[1,0,1]
	v_pk_fma_f32 v[64:65], v[110:111], v[70:71], v[64:65] op_sel_hi:[1,0,1]
	v_fma_f32 v31, -v27, v29, 1.0
	v_fmac_f32_e32 v29, v31, v29
	v_div_scale_f32 v31, vcc, v17, v13, v17
	v_mul_f32_e32 v33, v31, v29
	v_fma_f32 v35, -v27, v33, v31
	v_fmac_f32_e32 v33, v35, v29
	v_fma_f32 v27, -v27, v33, v31
	v_div_fmas_f32 v27, v27, v29, v33
	v_div_fixup_f32 v138, v27, v13, v17
	v_mul_f32_e32 v13, 0xbfb8aa3b, v21
	v_exp_f32_e32 v13, v13
	s_waitcnt vmcnt(6)
	v_pk_fma_f32 v[62:63], v[40:41], v[88:89], v[62:63] op_sel_hi:[1,0,1]
	v_pk_fma_f32 v[64:65], v[42:43], v[88:89], v[64:65] op_sel_hi:[1,0,1]
	s_waitcnt vmcnt(5)
	v_pk_fma_f32 v[62:63], v[112:113], v[90:91], v[62:63] op_sel_hi:[1,0,1]
	v_add_f32_e32 v13, 1.0, v13
	v_div_scale_f32 v17, s[4:5], v13, v13, v21
	v_rcp_f32_e32 v27, v17
	v_pk_fma_f32 v[64:65], v[114:115], v[90:91], v[64:65] op_sel_hi:[1,0,1]
	s_waitcnt vmcnt(4)
	v_pk_fma_f32 v[62:63], v[48:49], v[96:97], v[62:63] op_sel_hi:[1,0,1]
	v_pk_fma_f32 v[64:65], v[50:51], v[96:97], v[64:65] op_sel_hi:[1,0,1]
	v_fma_f32 v29, -v17, v27, 1.0
	v_fmac_f32_e32 v27, v29, v27
	v_div_scale_f32 v29, vcc, v21, v13, v21
	v_mul_f32_e32 v31, v29, v27
	v_fma_f32 v33, -v17, v31, v29
	v_fmac_f32_e32 v31, v33, v27
	v_fma_f32 v17, -v17, v31, v29
	s_waitcnt vmcnt(3)
	v_pk_fma_f32 v[62:63], v[116:117], v[98:99], v[62:63] op_sel_hi:[1,0,1]
	v_pk_fma_f32 v[64:65], v[118:119], v[98:99], v[64:65] op_sel_hi:[1,0,1]
	v_div_fmas_f32 v17, v17, v27, v31
	s_waitcnt vmcnt(2)
	v_pk_fma_f32 v[62:63], v[120:121], v[102:103], v[62:63] op_sel_hi:[1,0,1]
	v_pk_fma_f32 v[64:65], v[122:123], v[102:103], v[64:65] op_sel_hi:[1,0,1]
	v_div_fixup_f32 v140, v17, v13, v21
	s_waitcnt vmcnt(1)
	v_pk_fma_f32 v[62:63], v[124:125], v[12:13], v[62:63] op_sel_hi:[1,0,1]
	v_pk_fma_f32 v[12:13], v[126:127], v[12:13], v[64:65] op_sel_hi:[1,0,1]
	s_waitcnt vmcnt(0)
	v_pk_fma_f32 v[62:63], v[134:135], v[128:129], v[62:63] op_sel_hi:[1,0,1]
	v_pk_fma_f32 v[70:71], v[136:137], v[128:129], v[12:13] op_sel_hi:[1,0,1]
	v_pk_fma_f32 v[12:13], v[104:105], v[72:73], 0 op_sel_hi:[1,0,0]
	s_nop 0
	v_pk_fma_f32 v[12:13], v[36:37], v[78:79], v[12:13] op_sel_hi:[1,0,1]
	s_nop 0
	v_pk_fma_f32 v[12:13], v[108:109], v[82:83], v[12:13] op_sel_hi:[1,0,1]
	s_nop 0
	v_pk_fma_f32 v[12:13], v[40:41], v[86:87], v[12:13] op_sel_hi:[1,0,1]
	s_nop 0
	v_pk_fma_f32 v[12:13], v[112:113], v[28:29], v[12:13] op_sel_hi:[1,0,1]
	s_nop 0
	v_pk_fma_f32 v[12:13], v[48:49], v[94:95], v[12:13] op_sel_hi:[1,0,1]
	s_nop 0
	v_pk_fma_f32 v[12:13], v[116:117], v[30:31], v[12:13] op_sel_hi:[1,0,1]
	s_nop 0
	v_pk_fma_f32 v[12:13], v[120:121], v[100:101], v[12:13] op_sel_hi:[1,0,1]
	s_nop 0
	v_pk_fma_f32 v[12:13], v[124:125], v[16:17], v[12:13] op_sel_hi:[1,0,1]
	s_nop 0
	v_pk_fma_f32 v[68:69], v[134:135], v[138:139], v[12:13] op_sel_hi:[1,0,1]
	v_pk_fma_f32 v[12:13], v[106:107], v[72:73], 0 op_sel_hi:[1,0,0]
	s_nop 0
	v_pk_fma_f32 v[12:13], v[38:39], v[78:79], v[12:13] op_sel_hi:[1,0,1]
	s_nop 0
	v_pk_fma_f32 v[12:13], v[110:111], v[82:83], v[12:13] op_sel_hi:[1,0,1]
	s_nop 0
	v_pk_fma_f32 v[12:13], v[42:43], v[86:87], v[12:13] op_sel_hi:[1,0,1]
	s_nop 0
	v_pk_fma_f32 v[12:13], v[114:115], v[28:29], v[12:13] op_sel_hi:[1,0,1]
	s_nop 0
	v_pk_fma_f32 v[12:13], v[50:51], v[94:95], v[12:13] op_sel_hi:[1,0,1]
	s_nop 0
	v_pk_fma_f32 v[12:13], v[118:119], v[30:31], v[12:13] op_sel_hi:[1,0,1]
	s_nop 0
	v_pk_fma_f32 v[12:13], v[122:123], v[100:101], v[12:13] op_sel_hi:[1,0,1]
	s_nop 0
	v_pk_fma_f32 v[12:13], v[126:127], v[16:17], v[12:13] op_sel_hi:[1,0,1]
	s_nop 0
	v_pk_fma_f32 v[66:67], v[136:137], v[138:139], v[12:13] op_sel_hi:[1,0,1]
	v_pk_fma_f32 v[12:13], v[104:105], v[74:75], 0 op_sel_hi:[1,0,0]
	s_nop 0
	v_pk_fma_f32 v[12:13], v[36:37], v[76:77], v[12:13] op_sel_hi:[1,0,1]
	s_nop 0
	v_pk_fma_f32 v[12:13], v[108:109], v[80:81], v[12:13] op_sel_hi:[1,0,1]
	v_lshl_add_u64 v[108:109], v[46:47], 0, s[78:79]
	v_pk_fma_f32 v[12:13], v[40:41], v[84:85], v[12:13] op_sel_hi:[1,0,1]
	s_nop 0
	v_pk_fma_f32 v[12:13], v[112:113], v[32:33], v[12:13] op_sel_hi:[1,0,1]
	v_lshl_add_u64 v[112:113], v[46:47], 0, s[18:19]
	v_pk_fma_f32 v[12:13], v[48:49], v[92:93], v[12:13] op_sel_hi:[1,0,1]
	v_lshl_add_u64 v[48:49], v[46:47], 0, s[26:27]
	v_pk_fma_f32 v[12:13], v[116:117], v[26:27], v[12:13] op_sel_hi:[1,0,1]
	v_lshl_add_u64 v[116:117], v[46:47], 0, s[22:23]
	v_pk_fma_f32 v[12:13], v[120:121], v[34:35], v[12:13] op_sel_hi:[1,0,1]
	s_nop 0
	v_pk_fma_f32 v[12:13], v[124:125], v[20:21], v[12:13] op_sel_hi:[1,0,1]
	s_nop 0
	v_pk_fma_f32 v[64:65], v[134:135], v[140:141], v[12:13] op_sel_hi:[1,0,1]
	v_pk_fma_f32 v[12:13], v[106:107], v[74:75], 0 op_sel_hi:[1,0,0]
	s_nop 0
	v_pk_fma_f32 v[12:13], v[38:39], v[76:77], v[12:13] op_sel_hi:[1,0,1]
	s_nop 0
	v_pk_fma_f32 v[12:13], v[110:111], v[80:81], v[12:13] op_sel_hi:[1,0,1]
	v_lshl_add_u64 v[110:111], v[46:47], 0, s[16:17]
	v_pk_fma_f32 v[12:13], v[42:43], v[84:85], v[12:13] op_sel_hi:[1,0,1]
	global_load_dwordx4 v[40:43], v[24:25], off
	v_pk_fma_f32 v[12:13], v[114:115], v[32:33], v[12:13] op_sel_hi:[1,0,1]
	v_lshl_add_u64 v[114:115], v[46:47], 0, s[20:21]
	v_pk_fma_f32 v[12:13], v[50:51], v[92:93], v[12:13] op_sel_hi:[1,0,1]
	v_lshl_add_u64 v[50:51], v[46:47], 0, s[96:97]
	v_pk_fma_f32 v[12:13], v[118:119], v[26:27], v[12:13] op_sel_hi:[1,0,1]
	s_nop 0
	v_pk_fma_f32 v[12:13], v[122:123], v[34:35], v[12:13] op_sel_hi:[1,0,1]
	s_nop 0
	v_pk_fma_f32 v[12:13], v[126:127], v[20:21], v[12:13] op_sel_hi:[1,0,1]
	s_nop 0
	v_pk_fma_f32 v[16:17], v[136:137], v[140:141], v[12:13] op_sel_hi:[1,0,1]
	v_mul_f32_e32 v12, 0xbfb8aa3b, v14
	v_exp_f32_e32 v12, v12
	s_nop 0
	v_add_f32_e32 v12, 1.0, v12
	v_div_scale_f32 v13, s[4:5], v12, v12, v14
	v_rcp_f32_e32 v20, v13
	s_nop 0
	v_fma_f32 v21, -v13, v20, 1.0
	v_fmac_f32_e32 v20, v21, v20
	v_div_scale_f32 v21, vcc, v14, v12, v14
	v_mul_f32_e32 v26, v21, v20
	v_fma_f32 v27, -v13, v26, v21
	v_fmac_f32_e32 v26, v27, v20
	v_fma_f32 v13, -v13, v26, v21
	v_div_fmas_f32 v13, v13, v20, v26
	v_div_fixup_f32 v76, v13, v12, v14
	v_mul_f32_e32 v12, 0xbfb8aa3b, v18
	v_exp_f32_e32 v12, v12
	s_nop 0
	v_add_f32_e32 v12, 1.0, v12
	v_div_scale_f32 v13, s[4:5], v12, v12, v18
	v_rcp_f32_e32 v14, v13
	s_nop 0
	v_fma_f32 v20, -v13, v14, 1.0
	v_fmac_f32_e32 v14, v20, v14
	v_div_scale_f32 v20, vcc, v18, v12, v18
	v_mul_f32_e32 v21, v20, v14
	v_fma_f32 v26, -v13, v21, v20
	v_fmac_f32_e32 v21, v26, v14
	v_fma_f32 v13, -v13, v21, v20
	v_div_fmas_f32 v13, v13, v14, v21
	v_div_fixup_f32 v74, v13, v12, v18
	v_mul_f32_e32 v12, 0xbfb8aa3b, v22
	v_exp_f32_e32 v12, v12
	s_nop 0
	v_add_f32_e32 v12, 1.0, v12
	v_div_scale_f32 v13, s[4:5], v12, v12, v22
	v_rcp_f32_e32 v14, v13
	s_nop 0
	v_fma_f32 v18, -v13, v14, 1.0
	v_fmac_f32_e32 v14, v18, v14
	v_div_scale_f32 v18, vcc, v22, v12, v22
	v_mul_f32_e32 v20, v18, v14
	v_fma_f32 v21, -v13, v20, v18
	v_fmac_f32_e32 v20, v21, v14
	v_fma_f32 v13, -v13, v20, v18
	v_div_fmas_f32 v13, v13, v14, v20
	v_div_fixup_f32 v72, v13, v12, v22
	v_mul_f32_e32 v12, 0xbfb8aa3b, v15
	v_exp_f32_e32 v12, v12
	s_waitcnt vmcnt(0)
	v_pk_fma_f32 v[16:17], v[42:43], v[72:73], v[16:17] op_sel_hi:[1,0,1]
	v_add_f32_e32 v12, 1.0, v12
	v_div_scale_f32 v13, s[4:5], v12, v12, v15
	v_rcp_f32_e32 v14, v13
	s_nop 0
	v_fma_f32 v18, -v13, v14, 1.0
	v_fmac_f32_e32 v14, v18, v14
	v_div_scale_f32 v18, vcc, v15, v12, v15
	v_mul_f32_e32 v20, v18, v14
	v_fma_f32 v21, -v13, v20, v18
	v_fmac_f32_e32 v20, v21, v14
	v_fma_f32 v13, -v13, v20, v18
	v_div_fmas_f32 v13, v13, v14, v20
	v_div_fixup_f32 v82, v13, v12, v15
	v_mul_f32_e32 v12, 0xbfb8aa3b, v19
	v_exp_f32_e32 v12, v12
	s_nop 0
	v_add_f32_e32 v12, 1.0, v12
	v_div_scale_f32 v13, s[4:5], v12, v12, v19
	v_rcp_f32_e32 v14, v13
	s_nop 0
	v_fma_f32 v15, -v13, v14, 1.0
	v_fmac_f32_e32 v14, v15, v14
	v_div_scale_f32 v15, vcc, v19, v12, v19
	v_mul_f32_e32 v18, v15, v14
	v_fma_f32 v20, -v13, v18, v15
	v_fmac_f32_e32 v18, v20, v14
	v_fma_f32 v13, -v13, v18, v15
	v_div_fmas_f32 v13, v13, v14, v18
	v_div_fixup_f32 v80, v13, v12, v19
	v_mul_f32_e32 v12, 0xbfb8aa3b, v23
	v_exp_f32_e32 v12, v12
	s_nop 0
	v_add_f32_e32 v12, 1.0, v12
	v_div_scale_f32 v13, s[4:5], v12, v12, v23
	v_rcp_f32_e32 v14, v13
	s_nop 0
	v_fma_f32 v15, -v13, v14, 1.0
	v_fmac_f32_e32 v14, v15, v14
	v_div_scale_f32 v15, vcc, v23, v12, v23
	v_mul_f32_e32 v18, v15, v14
	v_fma_f32 v19, -v13, v18, v15
	v_fmac_f32_e32 v18, v19, v14
	v_fma_f32 v13, -v13, v18, v15
	v_div_fmas_f32 v13, v13, v14, v18
	v_div_fixup_f32 v78, v13, v12, v23
	v_mul_f32_e32 v12, 0xbfb8aa3b, v0
	v_exp_f32_e32 v12, v12
	s_nop 0
	v_add_f32_e32 v12, 1.0, v12
	v_div_scale_f32 v13, s[4:5], v12, v12, v0
	v_rcp_f32_e32 v14, v13
	s_nop 0
	v_fma_f32 v15, -v13, v14, 1.0
	v_fmac_f32_e32 v14, v15, v14
	v_div_scale_f32 v15, vcc, v0, v12, v0
	v_mul_f32_e32 v18, v15, v14
	v_fma_f32 v19, -v13, v18, v15
	v_fmac_f32_e32 v18, v19, v14
	v_fma_f32 v13, -v13, v18, v15
	v_div_fmas_f32 v13, v13, v14, v18
	v_div_fixup_f32 v84, v13, v12, v0
	v_mul_f32_e32 v0, 0xbfb8aa3b, v4
	v_exp_f32_e32 v0, v0
	s_nop 0
	v_add_f32_e32 v0, 1.0, v0
	v_div_scale_f32 v12, s[4:5], v0, v0, v4
	v_rcp_f32_e32 v13, v12
	s_nop 0
	v_fma_f32 v14, -v12, v13, 1.0
	v_fmac_f32_e32 v13, v14, v13
	v_div_scale_f32 v14, vcc, v4, v0, v4
	v_mul_f32_e32 v15, v14, v13
	v_fma_f32 v18, -v12, v15, v14
	v_fmac_f32_e32 v15, v18, v13
	v_fma_f32 v12, -v12, v15, v14
	v_div_fmas_f32 v12, v12, v13, v15
	v_div_fixup_f32 v86, v12, v0, v4
	v_mul_f32_e32 v0, 0xbfb8aa3b, v8
	v_exp_f32_e32 v0, v0
	v_lshl_add_u64 v[18:19], v[46:47], 0, s[24:25]
	v_add_f32_e32 v0, 1.0, v0
	v_div_scale_f32 v4, s[4:5], v0, v0, v8
	v_rcp_f32_e32 v12, v4
	s_nop 0
	v_fma_f32 v13, -v4, v12, 1.0
	v_fmac_f32_e32 v12, v13, v12
	v_div_scale_f32 v13, vcc, v8, v0, v8
	v_mul_f32_e32 v14, v13, v12
	v_fma_f32 v15, -v4, v14, v13
	v_fmac_f32_e32 v14, v15, v12
	v_fma_f32 v4, -v4, v14, v13
	v_div_fmas_f32 v4, v4, v12, v14
	v_div_fixup_f32 v88, v4, v0, v8
	v_mul_f32_e32 v0, 0xbfb8aa3b, v1
	v_exp_f32_e32 v0, v0
	s_nop 0
	v_add_f32_e32 v0, 1.0, v0
	v_div_scale_f32 v4, s[4:5], v0, v0, v1
	v_rcp_f32_e32 v8, v4
	s_nop 0
	v_fma_f32 v12, -v4, v8, 1.0
	v_fmac_f32_e32 v8, v12, v8
	v_div_scale_f32 v12, vcc, v1, v0, v1
	v_mul_f32_e32 v13, v12, v8
	v_fma_f32 v14, -v4, v13, v12
	v_fmac_f32_e32 v13, v14, v8
	v_fma_f32 v4, -v4, v13, v12
	v_div_fmas_f32 v4, v4, v8, v13
	v_div_fixup_f32 v94, v4, v0, v1
	v_mul_f32_e32 v0, 0xbfb8aa3b, v5
	v_exp_f32_e32 v0, v0
	s_nop 0
	v_add_f32_e32 v0, 1.0, v0
	v_div_scale_f32 v1, s[4:5], v0, v0, v5
	v_rcp_f32_e32 v4, v1
	s_nop 0
	v_fma_f32 v8, -v1, v4, 1.0
	v_fmac_f32_e32 v4, v8, v4
	v_div_scale_f32 v8, vcc, v5, v0, v5
	v_mul_f32_e32 v12, v8, v4
	v_fma_f32 v13, -v1, v12, v8
	v_fmac_f32_e32 v12, v13, v4
	v_fma_f32 v1, -v1, v12, v8
	v_div_fmas_f32 v1, v1, v4, v12
	v_div_fixup_f32 v92, v1, v0, v5
	v_mul_f32_e32 v0, 0xbfb8aa3b, v9
	v_exp_f32_e32 v0, v0
	s_nop 0
	v_add_f32_e32 v0, 1.0, v0
	v_div_scale_f32 v1, s[4:5], v0, v0, v9
	v_rcp_f32_e32 v4, v1
	s_nop 0
	v_fma_f32 v5, -v1, v4, 1.0
	v_fmac_f32_e32 v4, v5, v4
	v_div_scale_f32 v5, vcc, v9, v0, v9
	v_mul_f32_e32 v8, v5, v4
	v_fma_f32 v12, -v1, v8, v5
	v_fmac_f32_e32 v8, v12, v4
	v_fma_f32 v1, -v1, v8, v5
	v_div_fmas_f32 v1, v1, v4, v8
	v_div_fixup_f32 v90, v1, v0, v9
	v_mul_f32_e32 v0, 0xbfb8aa3b, v2
	v_exp_f32_e32 v0, v0
	s_nop 0
	v_add_f32_e32 v0, 1.0, v0
	v_div_scale_f32 v1, s[4:5], v0, v0, v2
	v_rcp_f32_e32 v4, v1
	s_nop 0
	v_fma_f32 v5, -v1, v4, 1.0
	v_fmac_f32_e32 v4, v5, v4
	v_div_scale_f32 v5, vcc, v2, v0, v2
	v_mul_f32_e32 v8, v5, v4
	v_fma_f32 v9, -v1, v8, v5
	v_fmac_f32_e32 v8, v9, v4
	v_fma_f32 v1, -v1, v8, v5
	v_div_fmas_f32 v1, v1, v4, v8
	v_div_fixup_f32 v100, v1, v0, v2
	v_mul_f32_e32 v0, 0xbfb8aa3b, v6
	v_exp_f32_e32 v0, v0
	s_nop 0
	v_add_f32_e32 v0, 1.0, v0
	v_div_scale_f32 v1, s[4:5], v0, v0, v6
	v_rcp_f32_e32 v2, v1
	s_nop 0
	v_fma_f32 v4, -v1, v2, 1.0
	v_fmac_f32_e32 v2, v4, v2
	v_div_scale_f32 v4, vcc, v6, v0, v6
	v_mul_f32_e32 v5, v4, v2
	v_fma_f32 v8, -v1, v5, v4
	v_fmac_f32_e32 v5, v8, v2
	v_fma_f32 v1, -v1, v5, v4
	v_div_fmas_f32 v1, v1, v2, v5
	v_div_fixup_f32 v98, v1, v0, v6
	v_mul_f32_e32 v0, 0xbfb8aa3b, v10
	v_exp_f32_e32 v0, v0
	s_nop 0
	v_add_f32_e32 v0, 1.0, v0
	v_div_scale_f32 v1, s[4:5], v0, v0, v10
	v_rcp_f32_e32 v2, v1
	s_nop 0
	v_fma_f32 v4, -v1, v2, 1.0
	v_fmac_f32_e32 v2, v4, v2
	v_div_scale_f32 v4, vcc, v10, v0, v10
	v_mul_f32_e32 v5, v4, v2
	v_fma_f32 v6, -v1, v5, v4
	v_fmac_f32_e32 v5, v6, v2
	v_fma_f32 v1, -v1, v5, v4
	v_div_fmas_f32 v1, v1, v2, v5
	v_div_fixup_f32 v96, v1, v0, v10
	v_mul_f32_e32 v0, 0xbfb8aa3b, v3
	v_exp_f32_e32 v0, v0
	s_nop 0
	v_add_f32_e32 v0, 1.0, v0
	v_div_scale_f32 v1, s[4:5], v0, v0, v3
	v_rcp_f32_e32 v2, v1
	s_nop 0
	v_fma_f32 v4, -v1, v2, 1.0
	v_fmac_f32_e32 v2, v4, v2
	v_div_scale_f32 v4, vcc, v3, v0, v3
	v_mul_f32_e32 v5, v4, v2
	v_fma_f32 v6, -v1, v5, v4
	v_fmac_f32_e32 v5, v6, v2
	v_fma_f32 v1, -v1, v5, v4
	v_div_fmas_f32 v1, v1, v2, v5
	v_div_fixup_f32 v106, v1, v0, v3
	v_mul_f32_e32 v0, 0xbfb8aa3b, v7
	v_exp_f32_e32 v0, v0
	s_nop 0
	v_add_f32_e32 v0, 1.0, v0
	v_div_scale_f32 v1, s[4:5], v0, v0, v7
	v_rcp_f32_e32 v2, v1
	s_nop 0
	v_fma_f32 v3, -v1, v2, 1.0
	v_fmac_f32_e32 v2, v3, v2
	v_div_scale_f32 v3, vcc, v7, v0, v7
	v_mul_f32_e32 v4, v3, v2
	v_fma_f32 v5, -v1, v4, v3
	v_fmac_f32_e32 v4, v5, v2
	v_fma_f32 v1, -v1, v4, v3
	v_div_fmas_f32 v1, v1, v2, v4
	v_div_fixup_f32 v104, v1, v0, v7
	v_mul_f32_e32 v0, 0xbfb8aa3b, v11
	v_exp_f32_e32 v0, v0
	s_nop 0
	v_add_f32_e32 v0, 1.0, v0
	v_div_scale_f32 v1, s[4:5], v0, v0, v11
	v_rcp_f32_e32 v2, v1
	s_nop 0
	v_fma_f32 v3, -v1, v2, 1.0
	v_fmac_f32_e32 v2, v3, v2
	v_div_scale_f32 v3, vcc, v11, v0, v11
	v_mul_f32_e32 v4, v3, v2
	v_fma_f32 v5, -v1, v4, v3
	v_fmac_f32_e32 v4, v5, v2
	v_fma_f32 v1, -v1, v4, v3
	v_div_fmas_f32 v1, v1, v2, v4
	v_div_fixup_f32 v102, v1, v0, v11
	global_load_dwordx4 v[0:3], v129, s[46:47] offset:112
	global_load_dwordx4 v[12:15], v129, s[46:47] offset:96
	global_load_dwordx4 v[28:31], v129, s[46:47] offset:80
	global_load_dwordx4 v[134:137], v129, s[46:47] offset:64
	s_waitcnt vmcnt(0)
	v_mul_f32_e32 v4, 0xbfb8aa3b, v134
	v_exp_f32_e32 v4, v4
	s_nop 0
	v_add_f32_e32 v4, 1.0, v4
	v_div_scale_f32 v5, s[4:5], v4, v4, v134
	v_rcp_f32_e32 v6, v5
	s_nop 0
	v_fma_f32 v7, -v5, v6, 1.0
	v_fmac_f32_e32 v6, v7, v6
	v_div_scale_f32 v7, vcc, v134, v4, v134
	v_mul_f32_e32 v8, v7, v6
	v_fma_f32 v9, -v5, v8, v7
	v_fmac_f32_e32 v8, v9, v6
	v_fma_f32 v5, -v5, v8, v7
	v_div_fmas_f32 v5, v5, v6, v8
	v_div_fixup_f32 v118, v5, v4, v134
	global_load_dwordx4 v[4:7], v129, s[10:11] offset:112
	global_load_dwordx4 v[20:23], v129, s[10:11] offset:96
	global_load_dwordx4 v[32:35], v129, s[10:11] offset:80
	global_load_dwordx4 v[138:141], v129, s[10:11] offset:64
	s_waitcnt vmcnt(0)
	v_mul_f32_e32 v8, 0xbfb8aa3b, v138
	v_exp_f32_e32 v8, v8
	s_nop 0
	v_add_f32_e32 v8, 1.0, v8
	v_div_scale_f32 v9, s[4:5], v8, v8, v138
	v_rcp_f32_e32 v10, v9
	v_readlane_b32 s4, v240, 41
	v_readlane_b32 s5, v240, 42
	v_fma_f32 v11, -v9, v10, 1.0
	v_fmac_f32_e32 v10, v11, v10
	v_div_scale_f32 v11, vcc, v138, v8, v138
	v_mul_f32_e32 v24, v11, v10
	v_fma_f32 v25, -v9, v24, v11
	v_fmac_f32_e32 v24, v25, v10
	v_fma_f32 v9, -v9, v24, v11
	v_div_fmas_f32 v9, v9, v10, v24
	v_div_fixup_f32 v120, v9, v8, v138
	global_load_dwordx4 v[8:11], v129, s[4:5] offset:48
	global_load_dwordx4 v[24:27], v129, s[4:5] offset:32
	global_load_dwordx4 v[36:39], v129, s[4:5] offset:16
	global_load_dwordx4 v[142:145], v129, s[4:5]
	s_waitcnt vmcnt(0)
	v_mul_f32_e32 v75, 0xbfb8aa3b, v142
	v_exp_f32_e32 v75, v75
	s_nop 0
	v_add_f32_e32 v75, 1.0, v75
	v_div_scale_f32 v77, s[4:5], v75, v75, v142
	v_rcp_f32_e32 v79, v77
	s_nop 0
	v_fma_f32 v81, -v77, v79, 1.0
	v_fmac_f32_e32 v79, v81, v79
	v_div_scale_f32 v81, vcc, v142, v75, v142
	v_mul_f32_e32 v83, v81, v79
	v_fma_f32 v85, -v77, v83, v81
	v_fmac_f32_e32 v83, v85, v79
	v_fma_f32 v77, -v77, v83, v81
	v_div_fmas_f32 v77, v77, v79, v83
	v_div_fixup_f32 v122, v77, v75, v142
	v_mul_f32_e32 v75, 0xbfb8aa3b, v135
	v_exp_f32_e32 v75, v75
	s_nop 0
	v_add_f32_e32 v75, 1.0, v75
	v_div_scale_f32 v77, s[4:5], v75, v75, v135
	v_rcp_f32_e32 v79, v77
	s_nop 0
	v_fma_f32 v81, -v77, v79, 1.0
	v_fmac_f32_e32 v79, v81, v79
	v_div_scale_f32 v81, vcc, v135, v75, v135
	v_mul_f32_e32 v83, v81, v79
	v_fma_f32 v85, -v77, v83, v81
	v_fmac_f32_e32 v83, v85, v79
	v_fma_f32 v77, -v77, v83, v81
	v_div_fmas_f32 v77, v77, v79, v83
	v_div_fixup_f32 v128, v77, v75, v135
	v_mul_f32_e32 v75, 0xbfb8aa3b, v139
	v_exp_f32_e32 v75, v75
	s_nop 0
	v_add_f32_e32 v75, 1.0, v75
	v_div_scale_f32 v77, s[4:5], v75, v75, v139
	v_rcp_f32_e32 v79, v77
	s_nop 0
	v_fma_f32 v81, -v77, v79, 1.0
	v_fmac_f32_e32 v79, v81, v79
	v_div_scale_f32 v81, vcc, v139, v75, v139
	v_mul_f32_e32 v83, v81, v79
	v_fma_f32 v85, -v77, v83, v81
	v_fmac_f32_e32 v83, v85, v79
	v_fma_f32 v77, -v77, v83, v81
	v_div_fmas_f32 v77, v77, v79, v83
	v_div_fixup_f32 v126, v77, v75, v139
	v_mul_f32_e32 v75, 0xbfb8aa3b, v143
	v_exp_f32_e32 v75, v75
	s_nop 0
	v_add_f32_e32 v75, 1.0, v75
	v_div_scale_f32 v77, s[4:5], v75, v75, v143
	v_rcp_f32_e32 v79, v77
	s_nop 0
	v_fma_f32 v81, -v77, v79, 1.0
	v_fmac_f32_e32 v79, v81, v79
	v_div_scale_f32 v81, vcc, v143, v75, v143
	v_mul_f32_e32 v83, v81, v79
	v_fma_f32 v85, -v77, v83, v81
	v_fmac_f32_e32 v83, v85, v79
	v_fma_f32 v77, -v77, v83, v81
	v_div_fmas_f32 v77, v77, v79, v83
	v_div_fixup_f32 v124, v77, v75, v143
	v_mul_f32_e32 v75, 0xbfb8aa3b, v136
	v_exp_f32_e32 v75, v75
	s_nop 0
	v_add_f32_e32 v75, 1.0, v75
	v_div_scale_f32 v77, s[4:5], v75, v75, v136
	v_rcp_f32_e32 v79, v77
	s_nop 0
	v_fma_f32 v81, -v77, v79, 1.0
	v_fmac_f32_e32 v79, v81, v79
	v_div_scale_f32 v81, vcc, v136, v75, v136
	v_mul_f32_e32 v83, v81, v79
	v_fma_f32 v85, -v77, v83, v81
	v_fmac_f32_e32 v83, v85, v79
	v_fma_f32 v77, -v77, v83, v81
	v_div_fmas_f32 v77, v77, v79, v83
	v_div_fixup_f32 v162, v77, v75, v136
	v_mul_f32_e32 v75, 0xbfb8aa3b, v140
	v_exp_f32_e32 v75, v75
	s_nop 0
	v_add_f32_e32 v75, 1.0, v75
	v_div_scale_f32 v77, s[4:5], v75, v75, v140
	v_rcp_f32_e32 v79, v77
	s_nop 0
	v_fma_f32 v81, -v77, v79, 1.0
	v_fmac_f32_e32 v79, v81, v79
	v_div_scale_f32 v81, vcc, v140, v75, v140
	v_mul_f32_e32 v83, v81, v79
	v_fma_f32 v85, -v77, v83, v81
	v_fmac_f32_e32 v83, v85, v79
	v_fma_f32 v77, -v77, v83, v81
	v_div_fmas_f32 v77, v77, v79, v83
	v_div_fixup_f32 v164, v77, v75, v140
	v_mul_f32_e32 v75, 0xbfb8aa3b, v144
	v_exp_f32_e32 v75, v75
	s_nop 0
	v_add_f32_e32 v75, 1.0, v75
	v_div_scale_f32 v77, s[4:5], v75, v75, v144
	v_rcp_f32_e32 v79, v77
	s_nop 0
	v_fma_f32 v81, -v77, v79, 1.0
	v_fmac_f32_e32 v79, v81, v79
	v_div_scale_f32 v81, vcc, v144, v75, v144
	v_mul_f32_e32 v83, v81, v79
	v_fma_f32 v85, -v77, v83, v81
	v_fmac_f32_e32 v83, v85, v79
	v_fma_f32 v77, -v77, v83, v81
	v_div_fmas_f32 v77, v77, v79, v83
	v_div_fixup_f32 v166, v77, v75, v144
	v_mul_f32_e32 v75, 0xbfb8aa3b, v137
	v_exp_f32_e32 v75, v75
	s_nop 0
	v_add_f32_e32 v75, 1.0, v75
	v_div_scale_f32 v77, s[4:5], v75, v75, v137
	v_rcp_f32_e32 v79, v77
	s_nop 0
	v_fma_f32 v81, -v77, v79, 1.0
	v_fmac_f32_e32 v79, v81, v79
	v_div_scale_f32 v81, vcc, v137, v75, v137
	v_mul_f32_e32 v83, v81, v79
	v_fma_f32 v85, -v77, v83, v81
	v_fmac_f32_e32 v83, v85, v79
	v_fma_f32 v77, -v77, v83, v81
	v_div_fmas_f32 v77, v77, v79, v83
	v_div_fixup_f32 v168, v77, v75, v137
	v_mul_f32_e32 v75, 0xbfb8aa3b, v141
	v_exp_f32_e32 v75, v75
	s_nop 0
	v_add_f32_e32 v75, 1.0, v75
	v_div_scale_f32 v77, s[4:5], v75, v75, v141
	v_rcp_f32_e32 v79, v77
	s_nop 0
	v_fma_f32 v81, -v77, v79, 1.0
	v_fmac_f32_e32 v79, v81, v79
	v_div_scale_f32 v81, vcc, v141, v75, v141
	v_mul_f32_e32 v83, v81, v79
	v_fma_f32 v85, -v77, v83, v81
	v_fmac_f32_e32 v83, v85, v79
	v_fma_f32 v77, -v77, v83, v81
	v_div_fmas_f32 v77, v77, v79, v83
	v_div_fixup_f32 v170, v77, v75, v141
	v_mul_f32_e32 v75, 0xbfb8aa3b, v145
	v_exp_f32_e32 v75, v75
	s_nop 0
	v_add_f32_e32 v75, 1.0, v75
	v_div_scale_f32 v77, s[4:5], v75, v75, v145
	v_rcp_f32_e32 v79, v77
	s_nop 0
	v_fma_f32 v81, -v77, v79, 1.0
	v_fmac_f32_e32 v79, v81, v79
	v_div_scale_f32 v81, vcc, v145, v75, v145
	v_mul_f32_e32 v83, v81, v79
	v_fma_f32 v85, -v77, v83, v81
	v_fmac_f32_e32 v83, v85, v79
	v_fma_f32 v77, -v77, v83, v81
	v_div_fmas_f32 v77, v77, v79, v83
	v_div_fixup_f32 v172, v77, v75, v145
	global_load_dwordx4 v[134:137], v[52:53], off
	s_nop 0
	global_load_dwordx4 v[52:55], v[54:55], off
	s_nop 0
	global_load_dwordx4 v[138:141], v[56:57], off
	global_load_dwordx4 v[142:145], v[58:59], off
	global_load_dwordx4 v[146:149], v[60:61], off
	global_load_dwordx4 v[150:153], v[108:109], off
	s_nop 0
	global_load_dwordx4 v[108:111], v[110:111], off
	s_nop 0
	global_load_dwordx4 v[154:157], v[112:113], off
	s_nop 0
	global_load_dwordx4 v[112:115], v[114:115], off
	s_nop 0
	global_load_dwordx4 v[158:161], v[116:117], off
	v_mul_f32_e32 v75, 0xbfb8aa3b, v28
	v_exp_f32_e32 v75, v75
	s_nop 0
	v_add_f32_e32 v75, 1.0, v75
	v_div_scale_f32 v77, s[4:5], v75, v75, v28
	v_rcp_f32_e32 v79, v77
	s_nop 0
	v_fma_f32 v81, -v77, v79, 1.0
	v_fmac_f32_e32 v79, v81, v79
	v_div_scale_f32 v81, vcc, v28, v75, v28
	v_mul_f32_e32 v83, v81, v79
	v_fma_f32 v85, -v77, v83, v81
	v_fmac_f32_e32 v83, v85, v79
	v_fma_f32 v77, -v77, v83, v81
	v_div_fmas_f32 v77, v77, v79, v83
	v_div_fixup_f32 v28, v77, v75, v28
	v_mul_f32_e32 v75, 0xbfb8aa3b, v32
	v_exp_f32_e32 v75, v75
	s_nop 0
	v_add_f32_e32 v75, 1.0, v75
	v_div_scale_f32 v77, s[4:5], v75, v75, v32
	v_rcp_f32_e32 v79, v77
	s_nop 0
	v_fma_f32 v81, -v77, v79, 1.0
	v_fmac_f32_e32 v79, v81, v79
	v_div_scale_f32 v81, vcc, v32, v75, v32
	v_mul_f32_e32 v83, v81, v79
	v_fma_f32 v85, -v77, v83, v81
	v_fmac_f32_e32 v83, v85, v79
	v_fma_f32 v77, -v77, v83, v81
	v_div_fmas_f32 v77, v77, v79, v83
	v_div_fixup_f32 v32, v77, v75, v32
	v_mul_f32_e32 v75, 0xbfb8aa3b, v36
	v_exp_f32_e32 v75, v75
	s_nop 0
	v_add_f32_e32 v75, 1.0, v75
	v_div_scale_f32 v77, s[4:5], v75, v75, v36
	v_rcp_f32_e32 v79, v77
	v_pk_fma_f32 v[58:59], v[42:43], v[74:75], v[66:67] op_sel_hi:[1,0,1]
	v_fma_f32 v81, -v77, v79, 1.0
	v_fmac_f32_e32 v79, v81, v79
	v_div_scale_f32 v81, vcc, v36, v75, v36
	v_mul_f32_e32 v83, v81, v79
	v_fma_f32 v85, -v77, v83, v81
	v_fmac_f32_e32 v83, v85, v79
	v_fma_f32 v77, -v77, v83, v81
	v_div_fmas_f32 v77, v77, v79, v83
	v_pk_fma_f32 v[56:57], v[40:41], v[76:77], v[62:63] op_sel_hi:[1,0,1]
	v_div_fixup_f32 v36, v77, v75, v36
	s_waitcnt vmcnt(9)
	v_pk_fma_f32 v[56:57], v[134:135], v[82:83], v[56:57] op_sel_hi:[1,0,1]
	s_waitcnt vmcnt(8)
	v_pk_fma_f32 v[56:57], v[52:53], v[84:85], v[56:57] op_sel_hi:[1,0,1]
	v_pk_fma_f32 v[16:17], v[136:137], v[78:79], v[16:17] op_sel_hi:[1,0,1]
	s_waitcnt vmcnt(7)
	v_pk_fma_f32 v[56:57], v[138:139], v[94:95], v[56:57] op_sel_hi:[1,0,1]
	v_pk_fma_f32 v[16:17], v[54:55], v[88:89], v[16:17] op_sel_hi:[1,0,1]
	s_waitcnt vmcnt(6)
	v_pk_fma_f32 v[56:57], v[142:143], v[100:101], v[56:57] op_sel_hi:[1,0,1]
	v_pk_fma_f32 v[16:17], v[140:141], v[90:91], v[16:17] op_sel_hi:[1,0,1]
	s_waitcnt vmcnt(5)
	v_pk_fma_f32 v[56:57], v[146:147], v[106:107], v[56:57] op_sel_hi:[1,0,1]
	v_pk_fma_f32 v[16:17], v[144:145], v[96:97], v[16:17] op_sel_hi:[1,0,1]
	s_waitcnt vmcnt(4)
	v_pk_fma_f32 v[56:57], v[150:151], v[118:119], v[56:57] op_sel_hi:[1,0,1]
	v_pk_fma_f32 v[16:17], v[148:149], v[102:103], v[16:17] op_sel_hi:[1,0,1]
	s_waitcnt vmcnt(3)
	v_pk_fma_f32 v[56:57], v[108:109], v[128:129], v[56:57] op_sel_hi:[1,0,1]
	v_pk_fma_f32 v[16:17], v[152:153], v[122:123], v[16:17] op_sel_hi:[1,0,1]
	s_waitcnt vmcnt(2)
	v_pk_fma_f32 v[56:57], v[154:155], v[162:163], v[56:57] op_sel_hi:[1,0,1]
	v_pk_fma_f32 v[16:17], v[110:111], v[124:125], v[16:17] op_sel_hi:[1,0,1]
	s_waitcnt vmcnt(1)
	v_pk_fma_f32 v[56:57], v[112:113], v[168:169], v[56:57] op_sel_hi:[1,0,1]
	v_pk_fma_f32 v[16:17], v[156:157], v[166:167], v[16:17] op_sel_hi:[1,0,1]
	s_waitcnt vmcnt(0)
	v_pk_fma_f32 v[62:63], v[158:159], v[28:29], v[56:57] op_sel_hi:[1,0,1]
	v_pk_fma_f32 v[56:57], v[42:43], v[76:77], v[70:71] op_sel_hi:[1,0,1]
	v_pk_fma_f32 v[58:59], v[136:137], v[80:81], v[58:59] op_sel_hi:[1,0,1]
	v_pk_fma_f32 v[56:57], v[136:137], v[82:83], v[56:57] op_sel_hi:[1,0,1]
	v_pk_fma_f32 v[16:17], v[114:115], v[172:173], v[16:17] op_sel_hi:[1,0,1]
	v_pk_fma_f32 v[56:57], v[54:55], v[84:85], v[56:57] op_sel_hi:[1,0,1]
	v_pk_fma_f32 v[58:59], v[54:55], v[86:87], v[58:59] op_sel_hi:[1,0,1]
	v_pk_fma_f32 v[56:57], v[140:141], v[94:95], v[56:57] op_sel_hi:[1,0,1]
	v_pk_fma_f32 v[54:55], v[160:161], v[36:37], v[16:17] op_sel_hi:[1,0,1]
	v_pk_fma_f32 v[56:57], v[144:145], v[100:101], v[56:57] op_sel_hi:[1,0,1]
	v_mul_f32_e32 v16, 0xbfb8aa3b, v29
	v_pk_fma_f32 v[56:57], v[148:149], v[106:107], v[56:57] op_sel_hi:[1,0,1]
	v_exp_f32_e32 v16, v16
	v_pk_fma_f32 v[56:57], v[152:153], v[118:119], v[56:57] op_sel_hi:[1,0,1]
	v_pk_fma_f32 v[58:59], v[140:141], v[92:93], v[58:59] op_sel_hi:[1,0,1]
	v_pk_fma_f32 v[56:57], v[110:111], v[128:129], v[56:57] op_sel_hi:[1,0,1]
	v_pk_fma_f32 v[58:59], v[144:145], v[98:99], v[58:59] op_sel_hi:[1,0,1]
	v_pk_fma_f32 v[56:57], v[156:157], v[162:163], v[56:57] op_sel_hi:[1,0,1]
	v_add_f32_e32 v16, 1.0, v16
	v_pk_fma_f32 v[56:57], v[114:115], v[168:169], v[56:57] op_sel_hi:[1,0,1]
	v_pk_fma_f32 v[58:59], v[148:149], v[104:105], v[58:59] op_sel_hi:[1,0,1]
	v_pk_fma_f32 v[60:61], v[160:161], v[28:29], v[56:57] op_sel_hi:[1,0,1]
	v_pk_fma_f32 v[56:57], v[40:41], v[74:75], v[68:69] op_sel_hi:[1,0,1]
	v_pk_fma_f32 v[40:41], v[40:41], v[72:73], v[64:65] op_sel_hi:[1,0,1]
	v_pk_fma_f32 v[56:57], v[134:135], v[80:81], v[56:57] op_sel_hi:[1,0,1]
	v_pk_fma_f32 v[40:41], v[134:135], v[78:79], v[40:41] op_sel_hi:[1,0,1]
	v_pk_fma_f32 v[56:57], v[52:53], v[86:87], v[56:57] op_sel_hi:[1,0,1]
	v_pk_fma_f32 v[40:41], v[52:53], v[88:89], v[40:41] op_sel_hi:[1,0,1]
	v_pk_fma_f32 v[56:57], v[138:139], v[92:93], v[56:57] op_sel_hi:[1,0,1]
	v_pk_fma_f32 v[40:41], v[138:139], v[90:91], v[40:41] op_sel_hi:[1,0,1]
	v_pk_fma_f32 v[56:57], v[142:143], v[98:99], v[56:57] op_sel_hi:[1,0,1]
	v_div_scale_f32 v17, s[4:5], v16, v16, v29
	v_pk_fma_f32 v[56:57], v[146:147], v[104:105], v[56:57] op_sel_hi:[1,0,1]
	v_pk_fma_f32 v[58:59], v[152:153], v[120:121], v[58:59] op_sel_hi:[1,0,1]
	v_pk_fma_f32 v[56:57], v[150:151], v[120:121], v[56:57] op_sel_hi:[1,0,1]
	v_pk_fma_f32 v[40:41], v[142:143], v[96:97], v[40:41] op_sel_hi:[1,0,1]
	v_rcp_f32_e32 v28, v17
	v_pk_fma_f32 v[56:57], v[108:109], v[126:127], v[56:57] op_sel_hi:[1,0,1]
	v_pk_fma_f32 v[58:59], v[110:111], v[126:127], v[58:59] op_sel_hi:[1,0,1]
	v_pk_fma_f32 v[40:41], v[146:147], v[102:103], v[40:41] op_sel_hi:[1,0,1]
	v_pk_fma_f32 v[56:57], v[154:155], v[164:165], v[56:57] op_sel_hi:[1,0,1]
	v_pk_fma_f32 v[58:59], v[156:157], v[164:165], v[58:59] op_sel_hi:[1,0,1]
	v_pk_fma_f32 v[40:41], v[150:151], v[122:123], v[40:41] op_sel_hi:[1,0,1]
	v_pk_fma_f32 v[56:57], v[112:113], v[170:171], v[56:57] op_sel_hi:[1,0,1]
	v_pk_fma_f32 v[58:59], v[114:115], v[170:171], v[58:59] op_sel_hi:[1,0,1]
	v_pk_fma_f32 v[40:41], v[108:109], v[124:125], v[40:41] op_sel_hi:[1,0,1]
	v_pk_fma_f32 v[56:57], v[158:159], v[32:33], v[56:57] op_sel_hi:[1,0,1]
	v_pk_fma_f32 v[58:59], v[160:161], v[32:33], v[58:59] op_sel_hi:[1,0,1]
	v_pk_fma_f32 v[40:41], v[154:155], v[166:167], v[40:41] op_sel_hi:[1,0,1]
	v_fma_f32 v32, -v17, v28, 1.0
	v_pk_fma_f32 v[40:41], v[112:113], v[172:173], v[40:41] op_sel_hi:[1,0,1]
	v_fmac_f32_e32 v28, v32, v28
	v_div_scale_f32 v32, vcc, v29, v16, v29
	v_pk_fma_f32 v[52:53], v[158:159], v[36:37], v[40:41] op_sel_hi:[1,0,1]
	v_mul_f32_e32 v36, v32, v28
	v_fma_f32 v40, -v17, v36, v32
	v_fmac_f32_e32 v36, v40, v28
	v_fma_f32 v17, -v17, v36, v32
	v_div_fmas_f32 v17, v17, v28, v36
	v_div_fixup_f32 v72, v17, v16, v29
	v_mul_f32_e32 v16, 0xbfb8aa3b, v33
	v_exp_f32_e32 v16, v16
	v_lshl_add_u64 v[40:41], v[46:47], 0, s[14:15]
	v_lshl_add_u64 v[42:43], v[46:47], 0, s[54:55]
	v_add_f32_e32 v16, 1.0, v16
	v_div_scale_f32 v17, s[4:5], v16, v16, v33
	v_rcp_f32_e32 v28, v17
	s_nop 0
	v_fma_f32 v29, -v17, v28, 1.0
	v_fmac_f32_e32 v28, v29, v28
	v_div_scale_f32 v29, vcc, v33, v16, v33
	v_mul_f32_e32 v32, v29, v28
	v_fma_f32 v36, -v17, v32, v29
	v_fmac_f32_e32 v32, v36, v28
	v_fma_f32 v17, -v17, v32, v29
	v_div_fmas_f32 v17, v17, v28, v32
	v_div_fixup_f32 v70, v17, v16, v33
	v_mul_f32_e32 v16, 0xbfb8aa3b, v37
	v_exp_f32_e32 v16, v16
	s_nop 0
	v_add_f32_e32 v16, 1.0, v16
	v_div_scale_f32 v17, s[4:5], v16, v16, v37
	v_rcp_f32_e32 v28, v17
	s_nop 0
	v_fma_f32 v29, -v17, v28, 1.0
	v_fmac_f32_e32 v28, v29, v28
	v_div_scale_f32 v29, vcc, v37, v16, v37
	v_mul_f32_e32 v32, v29, v28
	v_fma_f32 v33, -v17, v32, v29
	v_fmac_f32_e32 v32, v33, v28
	v_fma_f32 v17, -v17, v32, v29
	v_div_fmas_f32 v17, v17, v28, v32
	v_mul_f32_e32 v28, 0xbfb8aa3b, v30
	v_exp_f32_e32 v28, v28
	v_div_fixup_f32 v64, v17, v16, v37
	global_load_dwordx4 v[16:19], v[18:19], off
	v_add_f32_e32 v28, 1.0, v28
	v_div_scale_f32 v29, s[4:5], v28, v28, v30
	v_rcp_f32_e32 v32, v29
	s_nop 0
	v_fma_f32 v33, -v29, v32, 1.0
	v_fmac_f32_e32 v32, v33, v32
	v_div_scale_f32 v33, vcc, v30, v28, v30
	v_mul_f32_e32 v36, v33, v32
	v_fma_f32 v37, -v29, v36, v33
	v_fmac_f32_e32 v36, v37, v32
	v_fma_f32 v29, -v29, v36, v33
	v_div_fmas_f32 v29, v29, v32, v36
	v_div_fixup_f32 v76, v29, v28, v30
	v_mul_f32_e32 v28, 0xbfb8aa3b, v34
	v_exp_f32_e32 v28, v28
	s_nop 0
	v_add_f32_e32 v28, 1.0, v28
	v_div_scale_f32 v29, s[4:5], v28, v28, v34
	v_rcp_f32_e32 v30, v29
	s_nop 0
	v_fma_f32 v32, -v29, v30, 1.0
	v_fmac_f32_e32 v30, v32, v30
	v_div_scale_f32 v32, vcc, v34, v28, v34
	v_mul_f32_e32 v33, v32, v30
	v_fma_f32 v36, -v29, v33, v32
	v_fmac_f32_e32 v33, v36, v30
	v_fma_f32 v29, -v29, v33, v32
	v_div_fmas_f32 v29, v29, v30, v33
	v_div_fixup_f32 v74, v29, v28, v34
	v_mul_f32_e32 v28, 0xbfb8aa3b, v38
	v_exp_f32_e32 v28, v28
	v_lshl_add_u64 v[36:37], v[46:47], 0, s[76:77]
	v_add_f32_e32 v28, 1.0, v28
	v_div_scale_f32 v29, s[4:5], v28, v28, v38
	v_rcp_f32_e32 v30, v29
	s_nop 0
	v_fma_f32 v32, -v29, v30, 1.0
	v_fmac_f32_e32 v30, v32, v30
	v_div_scale_f32 v32, vcc, v38, v28, v38
	v_mul_f32_e32 v33, v32, v30
	v_fma_f32 v34, -v29, v33, v32
	v_fmac_f32_e32 v33, v34, v30
	v_fma_f32 v29, -v29, v33, v32
	v_div_fmas_f32 v29, v29, v30, v33
	v_div_fixup_f32 v66, v29, v28, v38
	v_mul_f32_e32 v28, 0xbfb8aa3b, v31
	v_exp_f32_e32 v28, v28
	s_nop 0
	v_add_f32_e32 v28, 1.0, v28
	v_div_scale_f32 v29, s[4:5], v28, v28, v31
	v_rcp_f32_e32 v30, v29
	s_nop 0
	v_fma_f32 v32, -v29, v30, 1.0
	v_fmac_f32_e32 v30, v32, v30
	v_div_scale_f32 v32, vcc, v31, v28, v31
	v_mul_f32_e32 v33, v32, v30
	v_fma_f32 v34, -v29, v33, v32
	v_fmac_f32_e32 v33, v34, v30
	v_fma_f32 v29, -v29, v33, v32
	v_div_fmas_f32 v29, v29, v30, v33
	v_div_fixup_f32 v80, v29, v28, v31
	v_mul_f32_e32 v28, 0xbfb8aa3b, v35
	v_exp_f32_e32 v28, v28
	s_nop 0
	v_add_f32_e32 v28, 1.0, v28
	v_div_scale_f32 v29, s[4:5], v28, v28, v35
	v_rcp_f32_e32 v30, v29
	s_nop 0
	v_fma_f32 v31, -v29, v30, 1.0
	v_fmac_f32_e32 v30, v31, v30
	v_div_scale_f32 v31, vcc, v35, v28, v35
	v_mul_f32_e32 v32, v31, v30
	v_fma_f32 v33, -v29, v32, v31
	v_fmac_f32_e32 v32, v33, v30
	v_fma_f32 v29, -v29, v32, v31
	v_div_fmas_f32 v29, v29, v30, v32
	v_div_fixup_f32 v78, v29, v28, v35
	v_mul_f32_e32 v28, 0xbfb8aa3b, v39
	v_exp_f32_e32 v28, v28
	v_lshl_add_u64 v[34:35], v[46:47], 0, s[34:35]
	v_add_f32_e32 v28, 1.0, v28
	v_div_scale_f32 v29, s[4:5], v28, v28, v39
	v_rcp_f32_e32 v30, v29
	s_nop 0
	v_fma_f32 v31, -v29, v30, 1.0
	v_fmac_f32_e32 v30, v31, v30
	v_div_scale_f32 v31, vcc, v39, v28, v39
	v_mul_f32_e32 v32, v31, v30
	v_fma_f32 v33, -v29, v32, v31
	v_fmac_f32_e32 v32, v33, v30
	v_fma_f32 v29, -v29, v32, v31
	v_div_fmas_f32 v29, v29, v30, v32
	v_div_fixup_f32 v68, v29, v28, v39
	v_lshl_add_u64 v[28:29], v[46:47], 0, s[28:29]
	v_lshl_add_u64 v[30:31], v[46:47], 0, s[38:39]
	v_lshl_add_u64 v[32:33], v[46:47], 0, s[8:9]
	v_lshl_add_u64 v[38:39], v[46:47], 0, s[12:13]
	v_mul_f32_e32 v46, 0xbfb8aa3b, v12
	v_exp_f32_e32 v46, v46
	s_nop 0
	v_add_f32_e32 v46, 1.0, v46
	v_div_scale_f32 v47, s[4:5], v46, v46, v12
	v_rcp_f32_e32 v65, v47
	s_nop 0
	v_fma_f32 v67, -v47, v65, 1.0
	v_fmac_f32_e32 v65, v67, v65
	v_div_scale_f32 v67, vcc, v12, v46, v12
	v_mul_f32_e32 v69, v67, v65
	v_fma_f32 v71, -v47, v69, v67
	v_fmac_f32_e32 v69, v71, v65
	v_fma_f32 v47, -v47, v69, v67
	v_div_fmas_f32 v47, v47, v65, v69
	v_div_fixup_f32 v86, v47, v46, v12
	v_mul_f32_e32 v12, 0xbfb8aa3b, v20
	v_exp_f32_e32 v12, v12
	s_nop 0
	v_add_f32_e32 v12, 1.0, v12
	v_div_scale_f32 v46, s[4:5], v12, v12, v20
	v_rcp_f32_e32 v47, v46
	s_nop 0
	v_fma_f32 v65, -v46, v47, 1.0
	v_fmac_f32_e32 v47, v65, v47
	v_div_scale_f32 v65, vcc, v20, v12, v20
	v_mul_f32_e32 v67, v65, v47
	v_fma_f32 v69, -v46, v67, v65
	v_fmac_f32_e32 v67, v69, v47
	v_fma_f32 v46, -v46, v67, v65
	v_div_fmas_f32 v46, v46, v47, v67
	v_div_fixup_f32 v84, v46, v12, v20
	v_mul_f32_e32 v12, 0xbfb8aa3b, v24
	v_exp_f32_e32 v12, v12
	s_nop 0
	v_add_f32_e32 v12, 1.0, v12
	v_div_scale_f32 v20, s[4:5], v12, v12, v24
	v_rcp_f32_e32 v46, v20
	s_nop 0
	v_fma_f32 v47, -v20, v46, 1.0
	v_fmac_f32_e32 v46, v47, v46
	v_div_scale_f32 v47, vcc, v24, v12, v24
	v_mul_f32_e32 v65, v47, v46
	v_fma_f32 v67, -v20, v65, v47
	v_fmac_f32_e32 v65, v67, v46
	v_fma_f32 v20, -v20, v65, v47
	v_div_fmas_f32 v20, v20, v46, v65
	v_div_fixup_f32 v46, v20, v12, v24
	v_mul_f32_e32 v12, 0xbfb8aa3b, v13
	v_exp_f32_e32 v12, v12
	s_nop 0
	v_add_f32_e32 v12, 1.0, v12
	v_div_scale_f32 v20, s[4:5], v12, v12, v13
	v_rcp_f32_e32 v24, v20
	s_nop 0
	v_fma_f32 v47, -v20, v24, 1.0
	v_fmac_f32_e32 v24, v47, v24
	v_div_scale_f32 v47, vcc, v13, v12, v13
	v_mul_f32_e32 v65, v47, v24
	v_fma_f32 v67, -v20, v65, v47
	v_fmac_f32_e32 v65, v67, v24
	v_fma_f32 v20, -v20, v65, v47
	v_div_fmas_f32 v20, v20, v24, v65
	v_div_fixup_f32 v94, v20, v12, v13
	v_mul_f32_e32 v12, 0xbfb8aa3b, v21
	v_exp_f32_e32 v12, v12
	s_nop 0
	v_add_f32_e32 v12, 1.0, v12
	v_div_scale_f32 v13, s[4:5], v12, v12, v21
	v_rcp_f32_e32 v20, v13
	s_nop 0
	v_fma_f32 v24, -v13, v20, 1.0
	v_fmac_f32_e32 v20, v24, v20
	v_div_scale_f32 v24, vcc, v21, v12, v21
	v_mul_f32_e32 v47, v24, v20
	v_fma_f32 v65, -v13, v47, v24
	v_fmac_f32_e32 v47, v65, v20
	v_fma_f32 v13, -v13, v47, v24
	v_div_fmas_f32 v13, v13, v20, v47
	v_div_fixup_f32 v92, v13, v12, v21
	v_mul_f32_e32 v12, 0xbfb8aa3b, v25
	v_exp_f32_e32 v12, v12
	s_nop 0
	v_add_f32_e32 v12, 1.0, v12
	v_div_scale_f32 v13, s[4:5], v12, v12, v25
	v_rcp_f32_e32 v20, v13
	s_nop 0
	v_fma_f32 v21, -v13, v20, 1.0
	v_fmac_f32_e32 v20, v21, v20
	v_div_scale_f32 v21, vcc, v25, v12, v25
	v_mul_f32_e32 v24, v21, v20
	v_fma_f32 v47, -v13, v24, v21
	v_fmac_f32_e32 v24, v47, v20
	v_fma_f32 v13, -v13, v24, v21
	v_div_fmas_f32 v13, v13, v20, v24
	v_div_fixup_f32 v82, v13, v12, v25
	v_mul_f32_e32 v12, 0xbfb8aa3b, v14
	v_exp_f32_e32 v12, v12
	s_nop 0
	v_add_f32_e32 v12, 1.0, v12
	v_div_scale_f32 v13, s[4:5], v12, v12, v14
	v_rcp_f32_e32 v20, v13
	s_nop 0
	v_fma_f32 v21, -v13, v20, 1.0
	v_fmac_f32_e32 v20, v21, v20
	v_div_scale_f32 v21, vcc, v14, v12, v14
	v_mul_f32_e32 v24, v21, v20
	v_fma_f32 v25, -v13, v24, v21
	v_fmac_f32_e32 v24, v25, v20
	v_fma_f32 v13, -v13, v24, v21
	v_div_fmas_f32 v13, v13, v20, v24
	v_div_fixup_f32 v100, v13, v12, v14
	v_mul_f32_e32 v12, 0xbfb8aa3b, v22
	v_exp_f32_e32 v12, v12
	s_nop 0
	v_add_f32_e32 v12, 1.0, v12
	v_div_scale_f32 v13, s[4:5], v12, v12, v22
	v_rcp_f32_e32 v14, v13
	s_nop 0
	v_fma_f32 v20, -v13, v14, 1.0
	v_fmac_f32_e32 v14, v20, v14
	v_div_scale_f32 v20, vcc, v22, v12, v22
	v_mul_f32_e32 v21, v20, v14
	v_fma_f32 v24, -v13, v21, v20
	v_fmac_f32_e32 v21, v24, v14
	v_fma_f32 v13, -v13, v21, v20
	v_div_fmas_f32 v13, v13, v14, v21
	v_div_fixup_f32 v98, v13, v12, v22
	v_mul_f32_e32 v12, 0xbfb8aa3b, v26
	v_exp_f32_e32 v12, v12
	s_nop 0
	v_add_f32_e32 v12, 1.0, v12
	v_div_scale_f32 v13, s[4:5], v12, v12, v26
	v_rcp_f32_e32 v14, v13
	s_nop 0
	v_fma_f32 v20, -v13, v14, 1.0
	v_fmac_f32_e32 v14, v20, v14
	v_div_scale_f32 v20, vcc, v26, v12, v26
	v_mul_f32_e32 v21, v20, v14
	v_fma_f32 v22, -v13, v21, v20
	v_fmac_f32_e32 v21, v22, v14
	v_fma_f32 v13, -v13, v21, v20
	v_div_fmas_f32 v13, v13, v14, v21
	v_div_fixup_f32 v88, v13, v12, v26
	v_mul_f32_e32 v12, 0xbfb8aa3b, v15
	v_exp_f32_e32 v12, v12
	s_nop 0
	v_add_f32_e32 v12, 1.0, v12
	v_div_scale_f32 v13, s[4:5], v12, v12, v15
	v_rcp_f32_e32 v14, v13
	s_nop 0
	v_fma_f32 v20, -v13, v14, 1.0
	v_fmac_f32_e32 v14, v20, v14
	v_div_scale_f32 v20, vcc, v15, v12, v15
	v_mul_f32_e32 v21, v20, v14
	v_fma_f32 v22, -v13, v21, v20
	v_fmac_f32_e32 v21, v22, v14
	v_fma_f32 v13, -v13, v21, v20
	v_div_fmas_f32 v13, v13, v14, v21
	v_div_fixup_f32 v104, v13, v12, v15
	v_mul_f32_e32 v12, 0xbfb8aa3b, v23
	v_exp_f32_e32 v12, v12
	s_nop 0
	v_add_f32_e32 v12, 1.0, v12
	v_div_scale_f32 v13, s[4:5], v12, v12, v23
	v_rcp_f32_e32 v14, v13
	s_nop 0
	v_fma_f32 v15, -v13, v14, 1.0
	v_fmac_f32_e32 v14, v15, v14
	v_div_scale_f32 v15, vcc, v23, v12, v23
	v_mul_f32_e32 v20, v15, v14
	v_fma_f32 v21, -v13, v20, v15
	v_fmac_f32_e32 v20, v21, v14
	v_fma_f32 v13, -v13, v20, v15
	v_div_fmas_f32 v13, v13, v14, v20
	v_div_fixup_f32 v102, v13, v12, v23
	v_mul_f32_e32 v12, 0xbfb8aa3b, v27
	v_exp_f32_e32 v12, v12
	s_nop 0
	v_add_f32_e32 v12, 1.0, v12
	v_div_scale_f32 v13, s[4:5], v12, v12, v27
	v_rcp_f32_e32 v14, v13
	s_nop 0
	v_fma_f32 v15, -v13, v14, 1.0
	v_fmac_f32_e32 v14, v15, v14
	v_div_scale_f32 v15, vcc, v27, v12, v27
	v_mul_f32_e32 v20, v15, v14
	v_fma_f32 v21, -v13, v20, v15
	v_fmac_f32_e32 v20, v21, v14
	v_fma_f32 v13, -v13, v20, v15
	v_div_fmas_f32 v13, v13, v14, v20
	v_div_fixup_f32 v90, v13, v12, v27
	v_mul_f32_e32 v12, 0xbfb8aa3b, v0
	v_exp_f32_e32 v12, v12
	s_nop 0
	v_add_f32_e32 v12, 1.0, v12
	v_div_scale_f32 v13, s[4:5], v12, v12, v0
	v_rcp_f32_e32 v14, v13
	s_nop 0
	v_fma_f32 v15, -v13, v14, 1.0
	v_fmac_f32_e32 v14, v15, v14
	v_div_scale_f32 v15, vcc, v0, v12, v0
	v_mul_f32_e32 v20, v15, v14
	v_fma_f32 v21, -v13, v20, v15
	v_fmac_f32_e32 v20, v21, v14
	v_fma_f32 v13, -v13, v20, v15
	v_div_fmas_f32 v13, v13, v14, v20
	v_div_fixup_f32 v108, v13, v12, v0
	v_mul_f32_e32 v0, 0xbfb8aa3b, v4
	v_exp_f32_e32 v0, v0
	s_nop 0
	v_add_f32_e32 v0, 1.0, v0
	v_div_scale_f32 v12, s[4:5], v0, v0, v4
	v_rcp_f32_e32 v13, v12
	s_nop 0
	v_fma_f32 v14, -v12, v13, 1.0
	v_fmac_f32_e32 v13, v14, v13
	v_div_scale_f32 v14, vcc, v4, v0, v4
	v_mul_f32_e32 v15, v14, v13
	v_fma_f32 v20, -v12, v15, v14
	v_fmac_f32_e32 v15, v20, v13
	v_fma_f32 v12, -v12, v15, v14
	v_div_fmas_f32 v12, v12, v13, v15
	v_div_fixup_f32 v112, v12, v0, v4
	v_mul_f32_e32 v0, 0xbfb8aa3b, v8
	v_exp_f32_e32 v0, v0
	s_nop 0
	v_add_f32_e32 v0, 1.0, v0
	v_div_scale_f32 v4, s[4:5], v0, v0, v8
	v_rcp_f32_e32 v12, v4
	s_nop 0
	v_fma_f32 v13, -v4, v12, 1.0
	v_fmac_f32_e32 v12, v13, v12
	v_div_scale_f32 v13, vcc, v8, v0, v8
	v_mul_f32_e32 v14, v13, v12
	v_fma_f32 v15, -v4, v14, v13
	v_fmac_f32_e32 v14, v15, v12
	v_fma_f32 v4, -v4, v14, v13
	v_div_fmas_f32 v4, v4, v12, v14
	v_div_fixup_f32 v96, v4, v0, v8
	v_mul_f32_e32 v0, 0xbfb8aa3b, v1
	v_exp_f32_e32 v0, v0
	s_nop 0
	v_add_f32_e32 v0, 1.0, v0
	v_div_scale_f32 v4, s[4:5], v0, v0, v1
	v_rcp_f32_e32 v8, v4
	s_nop 0
	v_fma_f32 v12, -v4, v8, 1.0
	v_fmac_f32_e32 v8, v12, v8
	v_div_scale_f32 v12, vcc, v1, v0, v1
	v_mul_f32_e32 v13, v12, v8
	v_fma_f32 v14, -v4, v13, v12
	v_fmac_f32_e32 v13, v14, v8
	v_fma_f32 v4, -v4, v13, v12
	v_div_fmas_f32 v4, v4, v8, v13
	v_div_fixup_f32 v118, v4, v0, v1
	v_mul_f32_e32 v0, 0xbfb8aa3b, v5
	v_exp_f32_e32 v0, v0
	s_nop 0
	v_add_f32_e32 v0, 1.0, v0
	v_div_scale_f32 v1, s[4:5], v0, v0, v5
	v_rcp_f32_e32 v4, v1
	s_nop 0
	v_fma_f32 v8, -v1, v4, 1.0
	v_fmac_f32_e32 v4, v8, v4
	v_div_scale_f32 v8, vcc, v5, v0, v5
	v_mul_f32_e32 v12, v8, v4
	v_fma_f32 v13, -v1, v12, v8
	v_fmac_f32_e32 v12, v13, v4
	v_fma_f32 v1, -v1, v12, v8
	v_div_fmas_f32 v1, v1, v4, v12
	v_div_fixup_f32 v116, v1, v0, v5
	v_mul_f32_e32 v0, 0xbfb8aa3b, v9
	v_exp_f32_e32 v0, v0
	s_nop 0
	v_add_f32_e32 v0, 1.0, v0
	v_div_scale_f32 v1, s[4:5], v0, v0, v9
	v_rcp_f32_e32 v4, v1
	s_nop 0
	v_fma_f32 v5, -v1, v4, 1.0
	v_fmac_f32_e32 v4, v5, v4
	v_div_scale_f32 v5, vcc, v9, v0, v9
	v_mul_f32_e32 v8, v5, v4
	v_fma_f32 v12, -v1, v8, v5
	v_fmac_f32_e32 v8, v12, v4
	v_fma_f32 v1, -v1, v8, v5
	v_div_fmas_f32 v1, v1, v4, v8
	v_div_fixup_f32 v106, v1, v0, v9
	v_mul_f32_e32 v0, 0xbfb8aa3b, v2
	v_exp_f32_e32 v0, v0
	s_nop 0
	v_add_f32_e32 v0, 1.0, v0
	v_div_scale_f32 v1, s[4:5], v0, v0, v2
	v_rcp_f32_e32 v4, v1
	s_nop 0
	v_fma_f32 v5, -v1, v4, 1.0
	v_fmac_f32_e32 v4, v5, v4
	v_div_scale_f32 v5, vcc, v2, v0, v2
	v_mul_f32_e32 v8, v5, v4
	v_fma_f32 v9, -v1, v8, v5
	v_fmac_f32_e32 v8, v9, v4
	v_fma_f32 v1, -v1, v8, v5
	v_div_fmas_f32 v1, v1, v4, v8
	v_div_fixup_f32 v120, v1, v0, v2
	v_mul_f32_e32 v0, 0xbfb8aa3b, v6
	v_exp_f32_e32 v0, v0
	s_nop 0
	v_add_f32_e32 v0, 1.0, v0
	v_div_scale_f32 v1, s[4:5], v0, v0, v6
	v_rcp_f32_e32 v2, v1
	s_nop 0
	v_fma_f32 v4, -v1, v2, 1.0
	v_fmac_f32_e32 v2, v4, v2
	v_div_scale_f32 v4, vcc, v6, v0, v6
	v_mul_f32_e32 v5, v4, v2
	v_fma_f32 v8, -v1, v5, v4
	v_fmac_f32_e32 v5, v8, v2
	v_fma_f32 v1, -v1, v5, v4
	v_div_fmas_f32 v1, v1, v2, v5
	v_div_fixup_f32 v122, v1, v0, v6
	v_mul_f32_e32 v0, 0xbfb8aa3b, v10
	v_exp_f32_e32 v0, v0
	s_waitcnt vmcnt(0)
	v_pk_fma_f32 v[8:9], v[16:17], v[72:73], v[62:63] op_sel_hi:[1,0,1]
	v_add_f32_e32 v0, 1.0, v0
	v_div_scale_f32 v1, s[4:5], v0, v0, v10
	v_rcp_f32_e32 v2, v1
	s_nop 0
	v_fma_f32 v4, -v1, v2, 1.0
	v_fmac_f32_e32 v2, v4, v2
	v_div_scale_f32 v4, vcc, v10, v0, v10
	v_mul_f32_e32 v5, v4, v2
	v_fma_f32 v6, -v1, v5, v4
	v_fmac_f32_e32 v5, v6, v2
	v_fma_f32 v1, -v1, v5, v4
	v_div_fmas_f32 v1, v1, v2, v5
	v_div_fixup_f32 v110, v1, v0, v10
	v_mul_f32_e32 v0, 0xbfb8aa3b, v3
	v_exp_f32_e32 v0, v0
	s_nop 0
	v_add_f32_e32 v0, 1.0, v0
	v_div_scale_f32 v1, s[4:5], v0, v0, v3
	v_rcp_f32_e32 v2, v1
	s_nop 0
	v_fma_f32 v4, -v1, v2, 1.0
	v_fmac_f32_e32 v2, v4, v2
	v_div_scale_f32 v4, vcc, v3, v0, v3
	v_mul_f32_e32 v5, v4, v2
	v_fma_f32 v6, -v1, v5, v4
	v_fmac_f32_e32 v5, v6, v2
	v_fma_f32 v1, -v1, v5, v4
	v_div_fmas_f32 v1, v1, v2, v5
	v_div_fixup_f32 v124, v1, v0, v3
	v_mul_f32_e32 v0, 0xbfb8aa3b, v7
	v_exp_f32_e32 v0, v0
	s_nop 0
	v_add_f32_e32 v0, 1.0, v0
	v_div_scale_f32 v1, s[4:5], v0, v0, v7
	v_rcp_f32_e32 v2, v1
	s_nop 0
	v_fma_f32 v3, -v1, v2, 1.0
	v_fmac_f32_e32 v2, v3, v2
	v_div_scale_f32 v3, vcc, v7, v0, v7
	v_mul_f32_e32 v4, v3, v2
	v_fma_f32 v5, -v1, v4, v3
	v_fmac_f32_e32 v4, v5, v2
	v_fma_f32 v1, -v1, v4, v3
	v_div_fmas_f32 v1, v1, v2, v4
	v_div_fixup_f32 v126, v1, v0, v7
	v_mul_f32_e32 v0, 0xbfb8aa3b, v11
	v_exp_f32_e32 v0, v0
	s_nop 0
	v_add_f32_e32 v0, 1.0, v0
	v_div_scale_f32 v1, s[4:5], v0, v0, v11
	v_rcp_f32_e32 v2, v1
	s_mul_i32 s4, s1, 3
	s_mul_i32 s1, s1, 0x12000
	s_mul_hi_u32 s5, s4, 0x6000
	v_fma_f32 v3, -v1, v2, 1.0
	v_fmac_f32_e32 v2, v3, v2
	v_div_scale_f32 v3, vcc, v11, v0, v11
	v_mul_f32_e32 v4, v3, v2
	v_fma_f32 v5, -v1, v4, v3
	v_fmac_f32_e32 v4, v5, v2
	v_fma_f32 v1, -v1, v4, v3
	v_div_fmas_f32 v1, v1, v2, v4
	v_div_fixup_f32 v114, v1, v0, v11
	global_load_dwordx4 v[0:3], v[48:49], off
	global_load_dwordx4 v[4:7], v[50:51], off
	v_pk_fma_f32 v[50:51], v[18:19], v[72:73], v[60:61] op_sel_hi:[1,0,1]
	s_add_u32 s4, s84, s1
	s_addc_u32 s5, s85, s5
	v_lshl_add_u64 v[44:45], s[4:5], 0, v[44:45]
	s_addk_i32 s0, 0x100
	s_cmp_lt_i32 s0, s0
	s_waitcnt vmcnt(1)
	v_pk_fma_f32 v[8:9], v[0:1], v[76:77], v[8:9] op_sel_hi:[1,0,1]
	s_waitcnt vmcnt(0)
	v_pk_fma_f32 v[48:49], v[4:5], v[80:81], v[8:9] op_sel_hi:[1,0,1]
	global_load_dwordx4 v[8:11], v[28:29], off
	global_load_dwordx4 v[12:15], v[30:31], off
	global_load_dwordx4 v[20:23], v[32:33], off
	global_load_dwordx4 v[24:27], v[34:35], off
	s_nop 0
	global_load_dwordx4 v[28:31], v[36:37], off
	global_load_dwordx4 v[32:35], v[38:39], off
	s_nop 0
	global_load_dwordx4 v[36:39], v[40:41], off
	s_nop 0
	global_load_dwordx4 v[40:43], v[42:43], off
	v_pk_fma_f32 v[50:51], v[2:3], v[76:77], v[50:51] op_sel_hi:[1,0,1]
	s_waitcnt vmcnt(7)
	v_pk_fma_f32 v[48:49], v[8:9], v[86:87], v[48:49] op_sel_hi:[1,0,1]
	v_pk_fma_f32 v[50:51], v[6:7], v[80:81], v[50:51] op_sel_hi:[1,0,1]
	s_waitcnt vmcnt(6)
	v_pk_fma_f32 v[48:49], v[12:13], v[94:95], v[48:49] op_sel_hi:[1,0,1]
	v_pk_fma_f32 v[50:51], v[10:11], v[86:87], v[50:51] op_sel_hi:[1,0,1]
	s_waitcnt vmcnt(5)
	v_pk_fma_f32 v[48:49], v[20:21], v[100:101], v[48:49] op_sel_hi:[1,0,1]
	v_pk_fma_f32 v[50:51], v[14:15], v[94:95], v[50:51] op_sel_hi:[1,0,1]
	s_waitcnt vmcnt(4)
	v_pk_fma_f32 v[48:49], v[24:25], v[104:105], v[48:49] op_sel_hi:[1,0,1]
	v_pk_fma_f32 v[50:51], v[22:23], v[100:101], v[50:51] op_sel_hi:[1,0,1]
	s_waitcnt vmcnt(3)
	v_pk_fma_f32 v[48:49], v[28:29], v[108:109], v[48:49] op_sel_hi:[1,0,1]
	v_pk_fma_f32 v[50:51], v[26:27], v[104:105], v[50:51] op_sel_hi:[1,0,1]
	s_waitcnt vmcnt(2)
	v_pk_fma_f32 v[48:49], v[32:33], v[118:119], v[48:49] op_sel_hi:[1,0,1]
	v_pk_fma_f32 v[50:51], v[30:31], v[108:109], v[50:51] op_sel_hi:[1,0,1]
	s_waitcnt vmcnt(1)
	v_pk_fma_f32 v[48:49], v[36:37], v[120:121], v[48:49] op_sel_hi:[1,0,1]
	v_pk_fma_f32 v[50:51], v[34:35], v[118:119], v[50:51] op_sel_hi:[1,0,1]
	s_waitcnt vmcnt(0)
	v_pk_fma_f32 v[48:49], v[40:41], v[124:125], v[48:49] op_sel_hi:[1,0,1]
	v_pk_fma_f32 v[50:51], v[38:39], v[120:121], v[50:51] op_sel_hi:[1,0,1]
	s_nop 0
	v_pk_fma_f32 v[50:51], v[42:43], v[124:125], v[50:51] op_sel_hi:[1,0,1]
	global_store_dwordx4 v[44:45], v[48:51], off
	s_nop 1
	v_pk_fma_f32 v[48:49], v[16:17], v[70:71], v[56:57] op_sel_hi:[1,0,1]
	v_pk_fma_f32 v[16:17], v[16:17], v[64:65], v[52:53] op_sel_hi:[1,0,1]
	v_pk_fma_f32 v[48:49], v[0:1], v[74:75], v[48:49] op_sel_hi:[1,0,1]
	v_pk_fma_f32 v[0:1], v[0:1], v[66:67], v[16:17] op_sel_hi:[1,0,1]
	v_pk_fma_f32 v[48:49], v[4:5], v[78:79], v[48:49] op_sel_hi:[1,0,1]
	v_pk_fma_f32 v[50:51], v[18:19], v[70:71], v[58:59] op_sel_hi:[1,0,1]
	v_pk_fma_f32 v[0:1], v[4:5], v[68:69], v[0:1] op_sel_hi:[1,0,1]
	v_pk_fma_f32 v[4:5], v[18:19], v[64:65], v[54:55] op_sel_hi:[1,0,1]
	v_pk_fma_f32 v[50:51], v[2:3], v[74:75], v[50:51] op_sel_hi:[1,0,1]
	v_pk_fma_f32 v[2:3], v[2:3], v[66:67], v[4:5] op_sel_hi:[1,0,1]
	v_pk_fma_f32 v[50:51], v[6:7], v[78:79], v[50:51] op_sel_hi:[1,0,1]
	v_pk_fma_f32 v[2:3], v[6:7], v[68:69], v[2:3] op_sel_hi:[1,0,1]
	v_pk_fma_f32 v[48:49], v[8:9], v[84:85], v[48:49] op_sel_hi:[1,0,1]
	v_pk_fma_f32 v[50:51], v[10:11], v[84:85], v[50:51] op_sel_hi:[1,0,1]
	v_pk_fma_f32 v[0:1], v[8:9], v[46:47], v[0:1] op_sel_hi:[1,0,1]
	v_pk_fma_f32 v[2:3], v[10:11], v[46:47], v[2:3] op_sel_hi:[1,0,1]
	v_pk_fma_f32 v[48:49], v[12:13], v[92:93], v[48:49] op_sel_hi:[1,0,1]
	v_pk_fma_f32 v[50:51], v[14:15], v[92:93], v[50:51] op_sel_hi:[1,0,1]
	v_pk_fma_f32 v[0:1], v[12:13], v[82:83], v[0:1] op_sel_hi:[1,0,1]
	v_pk_fma_f32 v[2:3], v[14:15], v[82:83], v[2:3] op_sel_hi:[1,0,1]
	v_pk_fma_f32 v[48:49], v[20:21], v[98:99], v[48:49] op_sel_hi:[1,0,1]
	v_pk_fma_f32 v[50:51], v[22:23], v[98:99], v[50:51] op_sel_hi:[1,0,1]
	v_pk_fma_f32 v[0:1], v[20:21], v[88:89], v[0:1] op_sel_hi:[1,0,1]
	v_pk_fma_f32 v[2:3], v[22:23], v[88:89], v[2:3] op_sel_hi:[1,0,1]
	v_pk_fma_f32 v[48:49], v[24:25], v[102:103], v[48:49] op_sel_hi:[1,0,1]
	v_pk_fma_f32 v[50:51], v[26:27], v[102:103], v[50:51] op_sel_hi:[1,0,1]
	v_pk_fma_f32 v[0:1], v[24:25], v[90:91], v[0:1] op_sel_hi:[1,0,1]
	v_pk_fma_f32 v[2:3], v[26:27], v[90:91], v[2:3] op_sel_hi:[1,0,1]
	v_pk_fma_f32 v[48:49], v[28:29], v[112:113], v[48:49] op_sel_hi:[1,0,1]
	v_pk_fma_f32 v[50:51], v[30:31], v[112:113], v[50:51] op_sel_hi:[1,0,1]
	v_add_co_u32_e32 v56, vcc, s33, v44
	v_pk_fma_f32 v[0:1], v[28:29], v[96:97], v[0:1] op_sel_hi:[1,0,1]
	v_pk_fma_f32 v[2:3], v[30:31], v[96:97], v[2:3] op_sel_hi:[1,0,1]
	v_pk_fma_f32 v[48:49], v[32:33], v[116:117], v[48:49] op_sel_hi:[1,0,1]
	v_pk_fma_f32 v[50:51], v[34:35], v[116:117], v[50:51] op_sel_hi:[1,0,1]
	v_addc_co_u32_e32 v57, vcc, 0, v45, vcc
	v_pk_fma_f32 v[0:1], v[32:33], v[106:107], v[0:1] op_sel_hi:[1,0,1]
	v_pk_fma_f32 v[2:3], v[34:35], v[106:107], v[2:3] op_sel_hi:[1,0,1]
	v_pk_fma_f32 v[48:49], v[36:37], v[122:123], v[48:49] op_sel_hi:[1,0,1]
	v_pk_fma_f32 v[50:51], v[38:39], v[122:123], v[50:51] op_sel_hi:[1,0,1]
	v_pk_fma_f32 v[0:1], v[36:37], v[110:111], v[0:1] op_sel_hi:[1,0,1]
	v_pk_fma_f32 v[2:3], v[38:39], v[110:111], v[2:3] op_sel_hi:[1,0,1]
	v_add_co_u32_e32 v4, vcc, 0xc000, v44
	v_pk_fma_f32 v[48:49], v[40:41], v[126:127], v[48:49] op_sel_hi:[1,0,1]
	v_pk_fma_f32 v[50:51], v[42:43], v[126:127], v[50:51] op_sel_hi:[1,0,1]
	v_pk_fma_f32 v[0:1], v[40:41], v[114:115], v[0:1] op_sel_hi:[1,0,1]
	v_pk_fma_f32 v[2:3], v[42:43], v[114:115], v[2:3] op_sel_hi:[1,0,1]
	v_addc_co_u32_e32 v5, vcc, 0, v45, vcc
	global_store_dwordx4 v[56:57], v[48:51], off
	global_store_dwordx4 v[4:5], v[0:3], off
	s_cbranch_scc1 .LBB0_135
.LBB0_136:
	v_writelane_b32 v239, s14, 25
	s_mov_b64 s[0:1], 0
	v_writelane_b32 v239, s15, 26
	v_writelane_b32 v239, s12, 27
	s_andn2_b64 vcc, exec, s[0:1]
	s_movk_i32 s55, 0x2a00
	v_writelane_b32 v239, s13, 28
	v_writelane_b32 v239, s76, 29
	s_nop 1
	v_writelane_b32 v239, s77, 30
	v_writelane_b32 v239, s34, 31
	s_nop 1
	v_writelane_b32 v239, s35, 32
	v_writelane_b32 v239, s8, 33
	s_nop 1
	v_writelane_b32 v239, s9, 34
	v_writelane_b32 v239, s38, 35
	s_nop 1
	v_writelane_b32 v239, s39, 36
	v_writelane_b32 v239, s28, 37
	s_nop 1
	v_writelane_b32 v239, s29, 38
	v_writelane_b32 v239, s96, 39
	s_nop 1
	v_writelane_b32 v239, s97, 40
	v_writelane_b32 v239, s26, 41
	s_nop 1
	v_writelane_b32 v239, s27, 42
	v_writelane_b32 v239, s24, 43
	s_nop 1
	v_writelane_b32 v239, s25, 44
	v_writelane_b32 v239, s22, 45
	s_nop 1
	v_writelane_b32 v239, s23, 46
	v_writelane_b32 v239, s20, 47
	s_nop 1
	v_writelane_b32 v239, s21, 48
	v_writelane_b32 v239, s18, 49
	s_nop 1
	v_writelane_b32 v239, s19, 50
	v_writelane_b32 v239, s16, 51
	s_nop 1
	v_writelane_b32 v239, s17, 52
	v_writelane_b32 v239, s78, 53
	s_nop 1
	v_writelane_b32 v239, s79, 54
	v_writelane_b32 v239, s74, 55
	s_nop 1
	v_writelane_b32 v239, s75, 56
	v_writelane_b32 v239, s72, 57
	s_nop 1
	v_writelane_b32 v239, s73, 58
	v_writelane_b32 v239, s70, 59
	s_nop 1
	v_writelane_b32 v239, s71, 60
	v_writelane_b32 v239, s66, 61
	s_nop 1
	v_writelane_b32 v239, s67, 62
	v_writelane_b32 v239, s48, 63
	s_nop 1
	v_writelane_b32 v238, s49, 0
	v_writelane_b32 v238, s42, 1
	s_nop 1
	v_writelane_b32 v238, s43, 2
	v_writelane_b32 v238, s40, 3
	s_nop 1
	v_writelane_b32 v238, s41, 4
	v_writelane_b32 v238, s36, 5
	s_nop 1
	v_writelane_b32 v238, s37, 6
	v_writelane_b32 v238, s6, 21
	s_nop 1
	v_writelane_b32 v238, s7, 22
	s_cbranch_vccnz .LBB0_171
	v_readlane_b32 s4, v241, 49
	s_mov_b64 s[0:1], 0xa80
	v_readlane_b32 s5, v241, 50
	s_andn2_b64 vcc, exec, s[4:5]
	v_readlane_b32 s1, v241, 57
	v_readlane_b32 s4, v241, 55
	v_readlane_b32 s5, v241, 56
	s_waitcnt vmcnt(0)
	v_mov_b32_e32 v0, s1
	v_readlane_b32 s6, v241, 58
	s_cbranch_vccnz .LBB0_140
	v_readlane_b32 s4, v241, 51
	v_readlane_b32 s5, v241, 52
	s_andn2_b64 vcc, exec, s[4:5]
	v_readlane_b32 s4, v241, 53
	s_mov_b64 s[0:1], 0x400
	v_readlane_b32 s6, v240, 49
	v_mov_b32_e32 v0, v176
	v_readlane_b32 s5, v241, 54
	s_cbranch_vccnz .LBB0_140
	v_readlane_b32 s4, v240, 43
	v_readlane_b32 s6, v240, 50
	v_mov_b32_e32 v0, v173
	v_readlane_b32 s0, v240, 51
	v_readlane_b32 s5, v240, 44
	v_readlane_b32 s1, v240, 52
